# D3 pipelined K-loop applied to the short-K (mla_b) GEMM loops as well
# speedup vs baseline: 1.0867x; 1.0016x over previous
.LBB0_398:
	s_andn2_b64 vcc, exec, s[0:1]
	s_cbranch_vccnz .LBB0_418
	s_add_i32 s0, s7, 0xfffffdc0
	s_and_b32 s1, s7, 7
	s_lshr_b32 s0, s0, 3
	s_mul_i32 s1, s1, 48
	s_add_i32 s1, s1, s0
	s_and_b32 s0, s1, 0xffff
	s_mul_i32 s0, s0, 0xaaab
	s_lshr_b32 s8, s0, 20
	s_mul_i32 s9, s8, 0xffffffe8
	s_add_i32 s1, s9, s1
	s_mul_i32 s9, s1, 0x2aab
	s_lshr_b32 s30, s9, 31
	s_lshr_b32 s9, s9, 16
	s_lshr_b32 s0, s0, 21
	s_add_i32 s9, s9, s30
	s_sext_i32_i16 s9, s9
	s_lshl_b32 s30, s0, 1
	s_add_i32 s30, s30, s9
	s_lshl_b32 s0, s0, 10
	s_lshl_b32 s9, s9, 8
	v_mov_b32_e32 v8, v188
	s_sub_i32 s8, s8, s30
	s_add_i32 s9, s9, s0
	s_mul_i32 s8, s8, 6
	v_ashrrev_i32_e32 v9, 3, v8
	v_add_u32_e32 v4, s9, v9
	s_movk_i32 s30, 0x300
	s_add_i32 s8, s8, s1
	v_mad_i64_i32 v[0:1], s[0:1], v4, s30, 0
	v_readlane_b32 s0, v255, 49
	v_readlane_b32 s1, v255, 50
	s_lshl_b32 s8, s8, 7
	v_add_u32_e32 v10, s8, v9
	v_mov_b64_e32 v[2:3], s[0:1]
	v_mad_i64_i32 v[2:3], s[0:1], v4, s30, v[2:3]
	v_lshlrev_b32_e32 v4, 4, v8
	v_and_b32_e32 v176, 0x70, v4
	v_mad_i64_i32 v[4:5], s[0:1], v10, s30, 0
	v_readlane_b32 s0, v255, 51
	v_readlane_b32 s1, v255, 52
	v_lshl_add_u64 v[2:3], v[2:3], 0, v[176:177]
	v_lshlrev_b32_e32 v12, 7, v8
	v_mov_b64_e32 v[6:7], s[0:1]
	v_mad_i64_i32 v[6:7], s[0:1], v10, s30, v[6:7]
	v_xor_b32_e32 v10, v9, v8
	v_lshlrev_b32_e32 v10, 4, v10
	v_lshl_add_u64 v[6:7], v[6:7], 0, v[176:177]
	v_and_b32_e32 v10, 0x70, v10
	v_lshl_or_b32 v176, v9, 7, v10
	v_lshrrev_b32_e32 v9, 4, v8
	v_bfe_u32 v14, v8, 4, 2
	v_and_b32_e32 v15, 7, v8
	v_add_co_u32_e32 v8, vcc, s77, v6
	v_bitop3_b32 v16, v9, v15, 3 bitop3:0x6c
	s_nop 0
	v_addc_co_u32_e32 v9, vcc, 0, v7, vcc
	v_add_co_u32_e32 v10, vcc, s28, v6
	s_mov_b32 s0, 0x2a000
	s_nop 0
	v_addc_co_u32_e32 v11, vcc, 0, v7, vcc
	global_load_dwordx4 v[68:71], v[8:9], off
	global_load_dwordx4 v[72:75], v[10:11], off
	v_add_co_u32_e32 v8, vcc, s54, v6
	v_and_b32_e32 v13, 0xffffc780, v12
	s_nop 0
	v_addc_co_u32_e32 v9, vcc, 0, v7, vcc
	v_add_co_u32_e32 v10, vcc, s0, v2
	s_mov_b32 s0, 0x24000
	s_nop 0
	v_addc_co_u32_e32 v11, vcc, 0, v3, vcc
	global_load_dwordx4 v[88:91], v[8:9], off
	global_load_dwordx4 v[96:99], v[10:11], off
	v_add_co_u32_e32 v8, vcc, s0, v2
	s_mov_b32 s0, 0x1e000
	s_nop 0
	v_addc_co_u32_e32 v9, vcc, 0, v3, vcc
	v_add_co_u32_e32 v10, vcc, s0, v2
	s_mov_b32 s0, 0x18000
	s_nop 0
	v_addc_co_u32_e32 v11, vcc, 0, v3, vcc
	global_load_dwordx4 v[108:111], v[8:9], off
	global_load_dwordx4 v[120:123], v[10:11], off
	v_add_co_u32_e32 v8, vcc, s0, v2
	v_and_b32_e32 v12, 0x2780, v12
	s_nop 0
	v_addc_co_u32_e32 v9, vcc, 0, v3, vcc
	v_add_co_u32_e32 v10, vcc, s77, v2
	v_bitop3_b32 v14, v14, v15, 4 bitop3:0x36
	s_nop 0
	v_addc_co_u32_e32 v11, vcc, 0, v3, vcc
	global_load_dwordx4 v[132:135], v[8:9], off
	global_load_dwordx4 v[136:139], v[10:11], off
	v_add_co_u32_e32 v8, vcc, s28, v2
	v_mov_b32_e32 v112, 0
	s_nop 0
	v_addc_co_u32_e32 v9, vcc, 0, v3, vcc
	v_add_co_u32_e32 v10, vcc, s54, v2
	s_mov_b64 s[0:1], 0
	s_nop 0
	v_addc_co_u32_e32 v11, vcc, 0, v3, vcc
	global_load_dwordx4 v[152:155], v[8:9], off
	global_load_dwordx4 v[160:163], v[10:11], off
	global_load_dwordx4 v[148:151], v[6:7], off
	global_load_dwordx4 v[168:171], v[2:3], off
	v_lshlrev_b32_e32 v2, 4, v16
	v_or_b32_e32 v185, v13, v2
	v_or_b32_e32 v184, v12, v2
	v_lshlrev_b32_e32 v2, 4, v14
	v_or_b32_e32 v183, v13, v2
	v_or_b32_e32 v182, v12, v2
	v_lshlrev_b32_e32 v2, 4, v15
	v_or_b32_e32 v0, v0, v2
	v_or_b32_e32 v4, v4, v2
	v_lshl_add_u64 v[178:179], s[34:35], 0, v[0:1]
	v_lshl_add_u64 v[180:181], s[84:85], 0, v[4:5]
	v_mov_b32_e32 v113, v112
	v_mov_b32_e32 v114, v112
	v_mov_b32_e32 v115, v112
	v_mov_b32_e32 v0, v112
	v_mov_b32_e32 v1, v112
	v_mov_b32_e32 v2, v112
	v_mov_b32_e32 v3, v112
	v_mov_b32_e32 v4, v112
	v_mov_b32_e32 v5, v112
	v_mov_b32_e32 v6, v112
	v_mov_b32_e32 v7, v112
	v_mov_b32_e32 v8, v112
	v_mov_b32_e32 v9, v112
	v_mov_b32_e32 v10, v112
	v_mov_b32_e32 v11, v112
	v_mov_b32_e32 v12, v112
	v_mov_b32_e32 v13, v112
	v_mov_b32_e32 v14, v112
	v_mov_b32_e32 v15, v112
	v_mov_b32_e32 v16, v112
	v_mov_b32_e32 v17, v112
	v_mov_b32_e32 v18, v112
	v_mov_b32_e32 v19, v112
	v_mov_b32_e32 v20, v112
	v_mov_b32_e32 v21, v112
	v_mov_b32_e32 v22, v112
	v_mov_b32_e32 v23, v112
	v_mov_b32_e32 v24, v112
	v_mov_b32_e32 v25, v112
	v_mov_b32_e32 v26, v112
	v_mov_b32_e32 v27, v112
	v_mov_b32_e32 v28, v112
	v_mov_b32_e32 v29, v112
	v_mov_b32_e32 v30, v112
	v_mov_b32_e32 v31, v112
	v_mov_b32_e32 v32, v112
	v_mov_b32_e32 v33, v112
	v_mov_b32_e32 v34, v112
	v_mov_b32_e32 v35, v112
	v_mov_b32_e32 v36, v112
	v_mov_b32_e32 v37, v112
	v_mov_b32_e32 v38, v112
	v_mov_b32_e32 v39, v112
	v_mov_b32_e32 v40, v112
	v_mov_b32_e32 v41, v112
	v_mov_b32_e32 v42, v112
	v_mov_b32_e32 v43, v112
	v_mov_b32_e32 v44, v112
	v_mov_b32_e32 v45, v112
	v_mov_b32_e32 v46, v112
	v_mov_b32_e32 v47, v112
	v_mov_b32_e32 v48, v112
	v_mov_b32_e32 v49, v112
	v_mov_b32_e32 v50, v112
	v_mov_b32_e32 v51, v112
	v_mov_b32_e32 v52, v112
	v_mov_b32_e32 v53, v112
	v_mov_b32_e32 v54, v112
	v_mov_b32_e32 v55, v112
	v_mov_b32_e32 v56, v112
	v_mov_b32_e32 v57, v112
	v_mov_b32_e32 v58, v112
	v_mov_b32_e32 v59, v112
	v_mov_b32_e32 v60, v112
	v_mov_b32_e32 v61, v112
	v_mov_b32_e32 v62, v112
	v_mov_b32_e32 v63, v112
	v_mov_b32_e32 v64, v112
	v_mov_b32_e32 v65, v112
	v_mov_b32_e32 v66, v112
	v_mov_b32_e32 v67, v112
	v_mov_b32_e32 v76, v112
	v_mov_b32_e32 v77, v112
	v_mov_b32_e32 v78, v112
	v_mov_b32_e32 v79, v112
	v_mov_b32_e32 v80, v112
	v_mov_b32_e32 v81, v112
	v_mov_b32_e32 v82, v112
	v_mov_b32_e32 v83, v112
	v_mov_b32_e32 v84, v112
	v_mov_b32_e32 v85, v112
	v_mov_b32_e32 v86, v112
	v_mov_b32_e32 v87, v112
	v_mov_b32_e32 v92, v112
	v_mov_b32_e32 v93, v112
	v_mov_b32_e32 v94, v112
	v_mov_b32_e32 v95, v112
	v_mov_b32_e32 v100, v112
	v_mov_b32_e32 v101, v112
	v_mov_b32_e32 v102, v112
	v_mov_b32_e32 v103, v112
	v_mov_b32_e32 v104, v112
	v_mov_b32_e32 v105, v112
	v_mov_b32_e32 v106, v112
	v_mov_b32_e32 v107, v112
	v_mov_b32_e32 v116, v112
	v_mov_b32_e32 v117, v112
	v_mov_b32_e32 v118, v112
	v_mov_b32_e32 v119, v112
	v_mov_b32_e32 v124, v112
	v_mov_b32_e32 v125, v112
	v_mov_b32_e32 v126, v112
	v_mov_b32_e32 v127, v112
	v_mov_b32_e32 v128, v112
	v_mov_b32_e32 v129, v112
	v_mov_b32_e32 v130, v112
	v_mov_b32_e32 v131, v112
	v_mov_b32_e32 v140, v112
	v_mov_b32_e32 v141, v112
	v_mov_b32_e32 v142, v112
	v_mov_b32_e32 v143, v112
	v_mov_b32_e32 v144, v112
	v_mov_b32_e32 v145, v112
	v_mov_b32_e32 v146, v112
	v_mov_b32_e32 v147, v112
	v_mov_b32_e32 v156, v112
	v_mov_b32_e32 v157, v112
	v_mov_b32_e32 v158, v112
	v_mov_b32_e32 v159, v112
	v_mov_b32_e32 v164, v112
	v_mov_b32_e32 v165, v112
	v_mov_b32_e32 v166, v112
	v_mov_b32_e32 v167, v112
	v_mov_b32_e32 v172, v112
	v_mov_b32_e32 v173, v112
	v_mov_b32_e32 v174, v112
	v_mov_b32_e32 v175, v112
	v_readlane_b32 s98, v253, 3
	v_readlane_b32 s99, v253, 4
	v_and_b32_e32 v224, 15, v188
	v_bfe_u32 v225, v188, 4, 2
	v_lshrrev_b32_e32 v226, 2, v224
	v_sub_u32_e32 v226, 0, v226
	v_and_b32_e32 v226, 3, v226
	v_xor_b32_e32 v225, v225, v226
	v_lshlrev_b32_e32 v225, 4, v225
	v_lshl_or_b32 v225, v224, 6, v225
	v_bfe_u32 v226, v188, 7, 1
	v_lshl_or_b32 v185, v226, 13, v225
	v_bfe_u32 v226, v188, 6, 1
	v_lshl_or_b32 v184, v226, 12, v225
	v_add_u32_e32 v184, 0x4000, v184
	v_lshrrev_b32_e32 v224, 3, v188
	v_bfe_u32 v225, v188, 2, 1
	v_lshrrev_b32_e32 v226, 2, v224
	v_sub_u32_e32 v226, 0, v226
	v_and_b32_e32 v226, 3, v226
	v_and_b32_e32 v227, 3, v188
	v_xor_b32_e32 v226, v227, v226
	v_lshlrev_b32_e32 v226, 4, v226
	v_xor_b32_e32 v224, v224, v225
	v_lshl_or_b32 v226, v224, 6, v226
	v_mul_u32_u24_e32 v225, 0x6000, v225
	v_add_u32_e32 v183, v225, v226
	s_mov_b32 m0, 0
	s_sub_u32 vcc_lo, s0, s98
	v_add_u32_e32 v186, vcc_lo, v178
	v_add_u32_e32 v187, vcc_lo, v180
	s_barrier
	s_waitcnt vmcnt(0)
	ds_write_b128 v183, v[168:171]
	ds_write_b128 v183, v[160:163] offset:2048
	ds_write_b128 v183, v[152:155] offset:4096
	ds_write_b128 v183, v[136:139] offset:6144
	ds_write_b128 v183, v[132:135] offset:8192
	ds_write_b128 v183, v[120:123] offset:10240
	ds_write_b128 v183, v[108:111] offset:12288
	ds_write_b128 v183, v[96:99] offset:14336
	ds_write_b128 v183, v[148:151] offset:16384
	ds_write_b128 v183, v[88:91] offset:18432
	ds_write_b128 v183, v[72:75] offset:20480
	ds_write_b128 v183, v[68:71] offset:22528
	v_cmp_gt_u32_e32 vcc, 0x6000, v183
	v_add_u32_e32 v182, 0xc000, v183
	v_add_u32_e32 v183, 0xffffa000, v183
	s_nop 0
	v_cndmask_b32_e32 v183, v183, v182, vcc
	v_add_u32_e32 v168, 0xa700000, v186
	global_load_dwordx4 v[168:171], v168, s[98:99] offset:128
	v_add_u32_e32 v160, 0xa706000, v186
	global_load_dwordx4 v[160:163], v160, s[98:99] offset:128
	v_add_u32_e32 v152, 0xa70c000, v186
	global_load_dwordx4 v[152:155], v152, s[98:99] offset:128
	v_add_u32_e32 v136, 0xa712000, v186
	global_load_dwordx4 v[136:139], v136, s[98:99] offset:128
	v_add_u32_e32 v132, 0xa718000, v186
	global_load_dwordx4 v[132:135], v132, s[98:99] offset:128
	v_add_u32_e32 v120, 0xa71e000, v186
	global_load_dwordx4 v[120:123], v120, s[98:99] offset:128
	v_add_u32_e32 v108, 0xa724000, v186
	global_load_dwordx4 v[108:111], v108, s[98:99] offset:128
	v_add_u32_e32 v96, 0xa72a000, v186
	global_load_dwordx4 v[96:99], v96, s[98:99] offset:128
	v_add_u32_e32 v148, 0x1f00000, v187
	global_load_dwordx4 v[148:151], v148, s[98:99] offset:128
	v_add_u32_e32 v88, 0x1f06000, v187
	global_load_dwordx4 v[88:91], v88, s[98:99] offset:128
	v_add_u32_e32 v72, 0x1f0c000, v187
	global_load_dwordx4 v[72:75], v72, s[98:99] offset:128
	v_add_u32_e32 v68, 0x1f12000, v187
	global_load_dwordx4 v[68:71], v68, s[98:99] offset:128
	s_add_u32 s0, s0, 0x80
	s_addc_u32 s1, s1, 0
.LBB0_400:
	s_waitcnt lgkmcnt(0)
	s_barrier
	ds_read_b128 v[224:227], v184
	ds_read_b128 v[228:231], v184 offset:1024
	ds_read_b128 v[232:235], v184 offset:2048
	ds_read_b128 v[236:239], v184 offset:3072
	ds_read_b128 v[190:193], v185
	ds_read_b128 v[194:197], v185 offset:1024
	ds_read_b128 v[198:201], v185 offset:2048
	ds_read_b128 v[204:207], v185 offset:3072
	ds_read_b128 v[208:211], v185 offset:4096
	ds_read_b128 v[212:215], v185 offset:5120
	ds_read_b128 v[216:219], v185 offset:6144
	ds_read_b128 v[220:223], v185 offset:7168
	s_movk_i32 vcc_lo, 0x6000
	s_cmp_eq_u32 m0, 2
	s_cselect_b32 vcc_lo, 0xffff4000, vcc_lo
	s_add_u32 m0, m0, 1
	s_cmp_eq_u32 m0, 3
	s_cselect_b32 m0, 0, m0
	v_add_u32_e32 v185, vcc_lo, v185
	v_add_u32_e32 v184, vcc_lo, v184
	v_xor_b32_e32 v185, 64, v185
	v_xor_b32_e32 v184, 64, v184
	s_waitcnt lgkmcnt(7)
	v_mfma_f32_16x16x32_bf16 v[172:175], v[224:227], v[190:193], v[172:175]
	v_mfma_f32_16x16x32_bf16 v[164:167], v[228:231], v[190:193], v[164:167]
	v_mfma_f32_16x16x32_bf16 v[156:159], v[232:235], v[190:193], v[156:159]
	v_mfma_f32_16x16x32_bf16 v[144:147], v[236:239], v[190:193], v[144:147]
	ds_read_b128 v[190:193], v185
	s_waitcnt lgkmcnt(7)
	v_mfma_f32_16x16x32_bf16 v[140:143], v[224:227], v[194:197], v[140:143]
	v_mfma_f32_16x16x32_bf16 v[128:131], v[228:231], v[194:197], v[128:131]
	v_mfma_f32_16x16x32_bf16 v[124:127], v[232:235], v[194:197], v[124:127]
	v_mfma_f32_16x16x32_bf16 v[116:119], v[236:239], v[194:197], v[116:119]
	ds_read_b128 v[194:197], v185 offset:1024
	s_waitcnt lgkmcnt(7)
	v_mfma_f32_16x16x32_bf16 v[104:107], v[224:227], v[198:201], v[104:107]
	v_mfma_f32_16x16x32_bf16 v[100:103], v[228:231], v[198:201], v[100:103]
	v_mfma_f32_16x16x32_bf16 v[92:95], v[232:235], v[198:201], v[92:95]
	v_mfma_f32_16x16x32_bf16 v[84:87], v[236:239], v[198:201], v[84:87]
	ds_read_b128 v[198:201], v185 offset:2048
	s_waitcnt lgkmcnt(7)
	v_mfma_f32_16x16x32_bf16 v[80:83], v[224:227], v[204:207], v[80:83]
	v_mfma_f32_16x16x32_bf16 v[76:79], v[228:231], v[204:207], v[76:79]
	v_mfma_f32_16x16x32_bf16 v[64:67], v[232:235], v[204:207], v[64:67]
	v_mfma_f32_16x16x32_bf16 v[60:63], v[236:239], v[204:207], v[60:63]
	ds_read_b128 v[204:207], v185 offset:3072
	s_waitcnt lgkmcnt(7)
	v_mfma_f32_16x16x32_bf16 v[56:59], v[224:227], v[208:211], v[56:59]
	v_mfma_f32_16x16x32_bf16 v[52:55], v[228:231], v[208:211], v[52:55]
	v_mfma_f32_16x16x32_bf16 v[48:51], v[232:235], v[208:211], v[48:51]
	v_mfma_f32_16x16x32_bf16 v[44:47], v[236:239], v[208:211], v[44:47]
	ds_read_b128 v[208:211], v185 offset:4096
	s_waitcnt lgkmcnt(7)
	v_mfma_f32_16x16x32_bf16 v[40:43], v[224:227], v[212:215], v[40:43]
	v_mfma_f32_16x16x32_bf16 v[36:39], v[228:231], v[212:215], v[36:39]
	v_mfma_f32_16x16x32_bf16 v[32:35], v[232:235], v[212:215], v[32:35]
	v_mfma_f32_16x16x32_bf16 v[28:31], v[236:239], v[212:215], v[28:31]
	ds_read_b128 v[212:215], v185 offset:5120
	s_waitcnt lgkmcnt(7)
	v_mfma_f32_16x16x32_bf16 v[24:27], v[224:227], v[216:219], v[24:27]
	v_mfma_f32_16x16x32_bf16 v[20:23], v[228:231], v[216:219], v[20:23]
	v_mfma_f32_16x16x32_bf16 v[16:19], v[232:235], v[216:219], v[16:19]
	v_mfma_f32_16x16x32_bf16 v[12:15], v[236:239], v[216:219], v[12:15]
	ds_read_b128 v[216:219], v185 offset:6144
	s_waitcnt lgkmcnt(7)
	v_mfma_f32_16x16x32_bf16 v[8:11], v[224:227], v[220:223], v[8:11]
	v_mfma_f32_16x16x32_bf16 v[4:7], v[228:231], v[220:223], v[4:7]
	v_mfma_f32_16x16x32_bf16 v[0:3], v[232:235], v[220:223], v[0:3]
	v_mfma_f32_16x16x32_bf16 v[112:115], v[236:239], v[220:223], v[112:115]
	ds_read_b128 v[220:223], v185 offset:7168
	ds_read_b128 v[224:227], v184
	ds_read_b128 v[228:231], v184 offset:1024
	ds_read_b128 v[232:235], v184 offset:2048
	ds_read_b128 v[236:239], v184 offset:3072
	s_movk_i32 vcc_lo, 0x6000
	s_cmp_eq_u32 m0, 2
	s_cselect_b32 vcc_lo, 0xffff4000, vcc_lo
	s_add_u32 m0, m0, 1
	s_cmp_eq_u32 m0, 3
	s_cselect_b32 m0, 0, m0
	v_add_u32_e32 v185, vcc_lo, v185
	v_add_u32_e32 v184, vcc_lo, v184
	v_xor_b32_e32 v185, 64, v185
	v_xor_b32_e32 v184, 64, v184
	s_sub_u32 vcc_lo, s0, s98
	v_add_u32_e32 v186, vcc_lo, v178
	v_add_u32_e32 v187, vcc_lo, v180
	s_barrier
	s_waitcnt lgkmcnt(0)
	v_mfma_f32_16x16x32_bf16 v[172:175], v[224:227], v[190:193], v[172:175]
	v_mfma_f32_16x16x32_bf16 v[164:167], v[228:231], v[190:193], v[164:167]
	v_mfma_f32_16x16x32_bf16 v[156:159], v[232:235], v[190:193], v[156:159]
	v_mfma_f32_16x16x32_bf16 v[144:147], v[236:239], v[190:193], v[144:147]
	s_waitcnt vmcnt(11)
	ds_write_b128 v183, v[168:171]
	v_add_u32_e32 v168, 0xa700000, v186
	global_load_dwordx4 v[168:171], v168, s[98:99] offset:128
	s_waitcnt vmcnt(11)
	ds_write_b128 v183, v[160:163] offset:2048
	v_add_u32_e32 v160, 0xa706000, v186
	global_load_dwordx4 v[160:163], v160, s[98:99] offset:128
	v_mfma_f32_16x16x32_bf16 v[140:143], v[224:227], v[194:197], v[140:143]
	v_mfma_f32_16x16x32_bf16 v[128:131], v[228:231], v[194:197], v[128:131]
	v_mfma_f32_16x16x32_bf16 v[124:127], v[232:235], v[194:197], v[124:127]
	v_mfma_f32_16x16x32_bf16 v[116:119], v[236:239], v[194:197], v[116:119]
	s_waitcnt vmcnt(11)
	ds_write_b128 v183, v[152:155] offset:4096
	v_add_u32_e32 v152, 0xa70c000, v186
	global_load_dwordx4 v[152:155], v152, s[98:99] offset:128
	v_mfma_f32_16x16x32_bf16 v[104:107], v[224:227], v[198:201], v[104:107]
	v_mfma_f32_16x16x32_bf16 v[100:103], v[228:231], v[198:201], v[100:103]
	v_mfma_f32_16x16x32_bf16 v[92:95], v[232:235], v[198:201], v[92:95]
	v_mfma_f32_16x16x32_bf16 v[84:87], v[236:239], v[198:201], v[84:87]
	s_waitcnt vmcnt(11)
	ds_write_b128 v183, v[136:139] offset:6144
	v_add_u32_e32 v136, 0xa712000, v186
	global_load_dwordx4 v[136:139], v136, s[98:99] offset:128
	s_waitcnt vmcnt(11)
	ds_write_b128 v183, v[132:135] offset:8192
	v_add_u32_e32 v132, 0xa718000, v186
	global_load_dwordx4 v[132:135], v132, s[98:99] offset:128
	v_mfma_f32_16x16x32_bf16 v[80:83], v[224:227], v[204:207], v[80:83]
	v_mfma_f32_16x16x32_bf16 v[76:79], v[228:231], v[204:207], v[76:79]
	v_mfma_f32_16x16x32_bf16 v[64:67], v[232:235], v[204:207], v[64:67]
	v_mfma_f32_16x16x32_bf16 v[60:63], v[236:239], v[204:207], v[60:63]
	s_waitcnt vmcnt(11)
	ds_write_b128 v183, v[120:123] offset:10240
	v_add_u32_e32 v120, 0xa71e000, v186
	global_load_dwordx4 v[120:123], v120, s[98:99] offset:128
	v_mfma_f32_16x16x32_bf16 v[56:59], v[224:227], v[208:211], v[56:59]
	v_mfma_f32_16x16x32_bf16 v[52:55], v[228:231], v[208:211], v[52:55]
	v_mfma_f32_16x16x32_bf16 v[48:51], v[232:235], v[208:211], v[48:51]
	v_mfma_f32_16x16x32_bf16 v[44:47], v[236:239], v[208:211], v[44:47]
	s_waitcnt vmcnt(11)
	ds_write_b128 v183, v[108:111] offset:12288
	v_add_u32_e32 v108, 0xa724000, v186
	global_load_dwordx4 v[108:111], v108, s[98:99] offset:128
	s_waitcnt vmcnt(11)
	ds_write_b128 v183, v[96:99] offset:14336
	v_add_u32_e32 v96, 0xa72a000, v186
	global_load_dwordx4 v[96:99], v96, s[98:99] offset:128
	v_mfma_f32_16x16x32_bf16 v[40:43], v[224:227], v[212:215], v[40:43]
	v_mfma_f32_16x16x32_bf16 v[36:39], v[228:231], v[212:215], v[36:39]
	v_mfma_f32_16x16x32_bf16 v[32:35], v[232:235], v[212:215], v[32:35]
	v_mfma_f32_16x16x32_bf16 v[28:31], v[236:239], v[212:215], v[28:31]
	s_waitcnt vmcnt(11)
	ds_write_b128 v183, v[148:151] offset:16384
	v_add_u32_e32 v148, 0x1f00000, v187
	global_load_dwordx4 v[148:151], v148, s[98:99] offset:128
	v_mfma_f32_16x16x32_bf16 v[24:27], v[224:227], v[216:219], v[24:27]
	v_mfma_f32_16x16x32_bf16 v[20:23], v[228:231], v[216:219], v[20:23]
	v_mfma_f32_16x16x32_bf16 v[16:19], v[232:235], v[216:219], v[16:19]
	v_mfma_f32_16x16x32_bf16 v[12:15], v[236:239], v[216:219], v[12:15]
	s_waitcnt vmcnt(11)
	ds_write_b128 v183, v[88:91] offset:18432
	v_add_u32_e32 v88, 0x1f06000, v187
	global_load_dwordx4 v[88:91], v88, s[98:99] offset:128
	s_waitcnt vmcnt(11)
	ds_write_b128 v183, v[72:75] offset:20480
	v_add_u32_e32 v72, 0x1f0c000, v187
	global_load_dwordx4 v[72:75], v72, s[98:99] offset:128
	v_mfma_f32_16x16x32_bf16 v[8:11], v[224:227], v[220:223], v[8:11]
	v_mfma_f32_16x16x32_bf16 v[4:7], v[228:231], v[220:223], v[4:7]
	v_mfma_f32_16x16x32_bf16 v[0:3], v[232:235], v[220:223], v[0:3]
	v_mfma_f32_16x16x32_bf16 v[112:115], v[236:239], v[220:223], v[112:115]
	s_waitcnt vmcnt(11)
	ds_write_b128 v183, v[68:71] offset:22528
	v_add_u32_e32 v68, 0x1f12000, v187
	global_load_dwordx4 v[68:71], v68, s[98:99] offset:128
	v_cmp_gt_u32_e32 vcc, 0x6000, v183
	v_add_u32_e32 v182, 0xc000, v183
	v_add_u32_e32 v183, 0xffffa000, v183
	s_nop 0
	v_cndmask_b32_e32 v183, v183, v182, vcc
	s_add_u32 s0, s0, 0x80
	s_addc_u32 s1, s1, 0
	s_cmpk_lg_i32 s0, 0x280
	s_cbranch_scc1 .LBB0_400
	s_waitcnt lgkmcnt(0)
	s_barrier
	ds_read_b128 v[224:227], v184
	ds_read_b128 v[228:231], v184 offset:1024
	ds_read_b128 v[232:235], v184 offset:2048
	ds_read_b128 v[236:239], v184 offset:3072
	ds_read_b128 v[190:193], v185
	ds_read_b128 v[194:197], v185 offset:1024
	ds_read_b128 v[198:201], v185 offset:2048
	ds_read_b128 v[204:207], v185 offset:3072
	ds_read_b128 v[208:211], v185 offset:4096
	ds_read_b128 v[212:215], v185 offset:5120
	ds_read_b128 v[216:219], v185 offset:6144
	ds_read_b128 v[220:223], v185 offset:7168
	s_movk_i32 vcc_lo, 0x6000
	s_cmp_eq_u32 m0, 2
	s_cselect_b32 vcc_lo, 0xffff4000, vcc_lo
	s_add_u32 m0, m0, 1
	s_cmp_eq_u32 m0, 3
	s_cselect_b32 m0, 0, m0
	v_add_u32_e32 v185, vcc_lo, v185
	v_add_u32_e32 v184, vcc_lo, v184
	v_xor_b32_e32 v185, 64, v185
	v_xor_b32_e32 v184, 64, v184
	s_waitcnt lgkmcnt(7)
	v_mfma_f32_16x16x32_bf16 v[172:175], v[224:227], v[190:193], v[172:175]
	v_mfma_f32_16x16x32_bf16 v[164:167], v[228:231], v[190:193], v[164:167]
	v_mfma_f32_16x16x32_bf16 v[156:159], v[232:235], v[190:193], v[156:159]
	v_mfma_f32_16x16x32_bf16 v[144:147], v[236:239], v[190:193], v[144:147]
	ds_read_b128 v[190:193], v185
	s_waitcnt lgkmcnt(7)
	v_mfma_f32_16x16x32_bf16 v[140:143], v[224:227], v[194:197], v[140:143]
	v_mfma_f32_16x16x32_bf16 v[128:131], v[228:231], v[194:197], v[128:131]
	v_mfma_f32_16x16x32_bf16 v[124:127], v[232:235], v[194:197], v[124:127]
	v_mfma_f32_16x16x32_bf16 v[116:119], v[236:239], v[194:197], v[116:119]
	ds_read_b128 v[194:197], v185 offset:1024
	s_waitcnt lgkmcnt(7)
	v_mfma_f32_16x16x32_bf16 v[104:107], v[224:227], v[198:201], v[104:107]
	v_mfma_f32_16x16x32_bf16 v[100:103], v[228:231], v[198:201], v[100:103]
	v_mfma_f32_16x16x32_bf16 v[92:95], v[232:235], v[198:201], v[92:95]
	v_mfma_f32_16x16x32_bf16 v[84:87], v[236:239], v[198:201], v[84:87]
	ds_read_b128 v[198:201], v185 offset:2048
	s_waitcnt lgkmcnt(7)
	v_mfma_f32_16x16x32_bf16 v[80:83], v[224:227], v[204:207], v[80:83]
	v_mfma_f32_16x16x32_bf16 v[76:79], v[228:231], v[204:207], v[76:79]
	v_mfma_f32_16x16x32_bf16 v[64:67], v[232:235], v[204:207], v[64:67]
	v_mfma_f32_16x16x32_bf16 v[60:63], v[236:239], v[204:207], v[60:63]
	ds_read_b128 v[204:207], v185 offset:3072
	s_waitcnt lgkmcnt(7)
	v_mfma_f32_16x16x32_bf16 v[56:59], v[224:227], v[208:211], v[56:59]
	v_mfma_f32_16x16x32_bf16 v[52:55], v[228:231], v[208:211], v[52:55]
	v_mfma_f32_16x16x32_bf16 v[48:51], v[232:235], v[208:211], v[48:51]
	v_mfma_f32_16x16x32_bf16 v[44:47], v[236:239], v[208:211], v[44:47]
	ds_read_b128 v[208:211], v185 offset:4096
	s_waitcnt lgkmcnt(7)
	v_mfma_f32_16x16x32_bf16 v[40:43], v[224:227], v[212:215], v[40:43]
	v_mfma_f32_16x16x32_bf16 v[36:39], v[228:231], v[212:215], v[36:39]
	v_mfma_f32_16x16x32_bf16 v[32:35], v[232:235], v[212:215], v[32:35]
	v_mfma_f32_16x16x32_bf16 v[28:31], v[236:239], v[212:215], v[28:31]
	ds_read_b128 v[212:215], v185 offset:5120
	s_waitcnt lgkmcnt(7)
	v_mfma_f32_16x16x32_bf16 v[24:27], v[224:227], v[216:219], v[24:27]
	v_mfma_f32_16x16x32_bf16 v[20:23], v[228:231], v[216:219], v[20:23]
	v_mfma_f32_16x16x32_bf16 v[16:19], v[232:235], v[216:219], v[16:19]
	v_mfma_f32_16x16x32_bf16 v[12:15], v[236:239], v[216:219], v[12:15]
	ds_read_b128 v[216:219], v185 offset:6144
	s_waitcnt lgkmcnt(7)
	v_mfma_f32_16x16x32_bf16 v[8:11], v[224:227], v[220:223], v[8:11]
	v_mfma_f32_16x16x32_bf16 v[4:7], v[228:231], v[220:223], v[4:7]
	v_mfma_f32_16x16x32_bf16 v[0:3], v[232:235], v[220:223], v[0:3]
	v_mfma_f32_16x16x32_bf16 v[112:115], v[236:239], v[220:223], v[112:115]
	ds_read_b128 v[220:223], v185 offset:7168
	ds_read_b128 v[224:227], v184
	ds_read_b128 v[228:231], v184 offset:1024
	ds_read_b128 v[232:235], v184 offset:2048
	ds_read_b128 v[236:239], v184 offset:3072
	s_movk_i32 vcc_lo, 0x6000
	s_cmp_eq_u32 m0, 2
	s_cselect_b32 vcc_lo, 0xffff4000, vcc_lo
	s_add_u32 m0, m0, 1
	s_cmp_eq_u32 m0, 3
	s_cselect_b32 m0, 0, m0
	v_add_u32_e32 v185, vcc_lo, v185
	v_add_u32_e32 v184, vcc_lo, v184
	v_xor_b32_e32 v185, 64, v185
	v_xor_b32_e32 v184, 64, v184
	s_waitcnt lgkmcnt(0)
	v_mfma_f32_16x16x32_bf16 v[172:175], v[224:227], v[190:193], v[172:175]
	v_mfma_f32_16x16x32_bf16 v[164:167], v[228:231], v[190:193], v[164:167]
	v_mfma_f32_16x16x32_bf16 v[156:159], v[232:235], v[190:193], v[156:159]
	v_mfma_f32_16x16x32_bf16 v[144:147], v[236:239], v[190:193], v[144:147]
	v_mfma_f32_16x16x32_bf16 v[140:143], v[224:227], v[194:197], v[140:143]
	v_mfma_f32_16x16x32_bf16 v[128:131], v[228:231], v[194:197], v[128:131]
	v_mfma_f32_16x16x32_bf16 v[124:127], v[232:235], v[194:197], v[124:127]
	v_mfma_f32_16x16x32_bf16 v[116:119], v[236:239], v[194:197], v[116:119]
	v_mfma_f32_16x16x32_bf16 v[104:107], v[224:227], v[198:201], v[104:107]
	v_mfma_f32_16x16x32_bf16 v[100:103], v[228:231], v[198:201], v[100:103]
	v_mfma_f32_16x16x32_bf16 v[92:95], v[232:235], v[198:201], v[92:95]
	v_mfma_f32_16x16x32_bf16 v[84:87], v[236:239], v[198:201], v[84:87]
	v_mfma_f32_16x16x32_bf16 v[80:83], v[224:227], v[204:207], v[80:83]
	v_mfma_f32_16x16x32_bf16 v[76:79], v[228:231], v[204:207], v[76:79]
	v_mfma_f32_16x16x32_bf16 v[64:67], v[232:235], v[204:207], v[64:67]
	v_mfma_f32_16x16x32_bf16 v[60:63], v[236:239], v[204:207], v[60:63]
	v_mfma_f32_16x16x32_bf16 v[56:59], v[224:227], v[208:211], v[56:59]
	v_mfma_f32_16x16x32_bf16 v[52:55], v[228:231], v[208:211], v[52:55]
	v_mfma_f32_16x16x32_bf16 v[48:51], v[232:235], v[208:211], v[48:51]
	v_mfma_f32_16x16x32_bf16 v[44:47], v[236:239], v[208:211], v[44:47]
	v_mfma_f32_16x16x32_bf16 v[40:43], v[224:227], v[212:215], v[40:43]
	v_mfma_f32_16x16x32_bf16 v[36:39], v[228:231], v[212:215], v[36:39]
	v_mfma_f32_16x16x32_bf16 v[32:35], v[232:235], v[212:215], v[32:35]
	v_mfma_f32_16x16x32_bf16 v[28:31], v[236:239], v[212:215], v[28:31]
	v_mfma_f32_16x16x32_bf16 v[24:27], v[224:227], v[216:219], v[24:27]
	v_mfma_f32_16x16x32_bf16 v[20:23], v[228:231], v[216:219], v[20:23]
	v_mfma_f32_16x16x32_bf16 v[16:19], v[232:235], v[216:219], v[16:19]
	v_mfma_f32_16x16x32_bf16 v[12:15], v[236:239], v[216:219], v[12:15]
	v_mfma_f32_16x16x32_bf16 v[8:11], v[224:227], v[220:223], v[8:11]
	v_mfma_f32_16x16x32_bf16 v[4:7], v[228:231], v[220:223], v[4:7]
	v_mfma_f32_16x16x32_bf16 v[0:3], v[232:235], v[220:223], v[0:3]
	v_mfma_f32_16x16x32_bf16 v[112:115], v[236:239], v[220:223], v[112:115]
	v_lshrrev_b32_e32 v224, 4, v188
	v_and_b32_e32 v225, 7, v188
	v_bitop3_b32 v226, v224, v225, 3 bitop3:0x6c
	v_lshlrev_b32_e32 v227, 7, v188
	v_bfe_u32 v228, v188, 4, 2
	v_and_b32_e32 v229, 0xffffc780, v227
	v_and_b32_e32 v227, 0x2780, v227
	v_bitop3_b32 v228, v228, v225, 4 bitop3:0x36
	v_lshlrev_b32_e32 v226, 4, v226
	v_lshlrev_b32_e32 v228, 4, v228
	v_or_b32_e32 v185, v229, v226
	v_or_b32_e32 v184, v227, v226
	v_or_b32_e32 v183, v229, v228
	v_or_b32_e32 v182, v227, v228
	s_waitcnt vmcnt(0)
	s_barrier
	s_waitcnt vmcnt(11)
	ds_write_b128 v176, v[168:171]
	s_waitcnt vmcnt(10)
	ds_write_b128 v176, v[160:163] offset:4096
	s_waitcnt vmcnt(9)
	ds_write_b128 v176, v[152:155] offset:8192
	s_waitcnt vmcnt(8)
	ds_write_b128 v176, v[136:139] offset:12288
	s_waitcnt vmcnt(7)
	ds_write_b128 v176, v[132:135] offset:16384
	s_waitcnt vmcnt(6)
	ds_write_b128 v176, v[120:123] offset:20480
	s_waitcnt vmcnt(5)
	ds_write_b128 v176, v[108:111] offset:24576
	s_waitcnt vmcnt(4)
	ds_write_b128 v176, v[96:99] offset:28672
	s_waitcnt vmcnt(3)
	ds_write_b128 v176, v[148:151] offset:32768
	s_waitcnt vmcnt(2)
	ds_write_b128 v176, v[88:91] offset:36864
	s_waitcnt vmcnt(1)
	ds_write_b128 v176, v[72:75] offset:40960
	s_waitcnt vmcnt(0)
	ds_write_b128 v176, v[68:71] offset:45056
	s_waitcnt lgkmcnt(0)
	s_barrier
	ds_read_b128 v[68:71], v185
	ds_read_b128 v[72:75], v185 offset:2048
	ds_read_b128 v[88:91], v185 offset:4096
	ds_read_b128 v[96:99], v185 offset:6144
	ds_read_b128 v[108:111], v185 offset:8192
	ds_read_b128 v[120:123], v185 offset:10240
	ds_read_b128 v[132:135], v185 offset:12288
	ds_read_b128 v[136:139], v185 offset:14336
	ds_read_b128 v[148:151], v184 offset:32768
	ds_read_b128 v[152:155], v184 offset:34816
	ds_read_b128 v[160:163], v184 offset:36864
	ds_read_b128 v[168:171], v184 offset:38912
	s_waitcnt lgkmcnt(3)
	v_mfma_f32_16x16x32_bf16 v[172:175], v[148:151], v[68:71], v[172:175]
	s_waitcnt lgkmcnt(2)
	v_mfma_f32_16x16x32_bf16 v[164:167], v[152:155], v[68:71], v[164:167]
	s_waitcnt lgkmcnt(1)
	v_mfma_f32_16x16x32_bf16 v[156:159], v[160:163], v[68:71], v[156:159]
	s_waitcnt lgkmcnt(0)
	v_mfma_f32_16x16x32_bf16 v[68:71], v[168:171], v[68:71], v[144:147]
	v_mfma_f32_16x16x32_bf16 v[140:143], v[148:151], v[72:75], v[140:143]
	v_mfma_f32_16x16x32_bf16 v[128:131], v[152:155], v[72:75], v[128:131]
	v_mfma_f32_16x16x32_bf16 v[144:147], v[160:163], v[72:75], v[124:127]
	v_mfma_f32_16x16x32_bf16 v[72:75], v[168:171], v[72:75], v[116:119]
	v_mfma_f32_16x16x32_bf16 v[64:67], v[160:163], v[96:99], v[64:67]
	v_mfma_f32_16x16x32_bf16 v[60:63], v[168:171], v[96:99], v[60:63]
	v_mfma_f32_16x16x32_bf16 v[56:59], v[148:151], v[108:111], v[56:59]
	v_mfma_f32_16x16x32_bf16 v[52:55], v[152:155], v[108:111], v[52:55]
	v_mfma_f32_16x16x32_bf16 v[48:51], v[160:163], v[108:111], v[48:51]
	v_mfma_f32_16x16x32_bf16 v[44:47], v[168:171], v[108:111], v[44:47]
	v_mfma_f32_16x16x32_bf16 v[40:43], v[148:151], v[120:123], v[40:43]
	v_mfma_f32_16x16x32_bf16 v[36:39], v[152:155], v[120:123], v[36:39]
	v_mfma_f32_16x16x32_bf16 v[32:35], v[160:163], v[120:123], v[32:35]
	v_mfma_f32_16x16x32_bf16 v[28:31], v[168:171], v[120:123], v[28:31]
	v_mfma_f32_16x16x32_bf16 v[24:27], v[148:151], v[132:135], v[24:27]
	v_mfma_f32_16x16x32_bf16 v[20:23], v[152:155], v[132:135], v[20:23]
	v_mfma_f32_16x16x32_bf16 v[16:19], v[160:163], v[132:135], v[16:19]
	v_mfma_f32_16x16x32_bf16 v[12:15], v[168:171], v[132:135], v[12:15]
	v_mfma_f32_16x16x32_bf16 v[8:11], v[148:151], v[136:139], v[8:11]
	v_mfma_f32_16x16x32_bf16 v[4:7], v[152:155], v[136:139], v[4:7]
	v_mfma_f32_16x16x32_bf16 v[0:3], v[160:163], v[136:139], v[0:3]
	v_mfma_f32_16x16x32_bf16 v[178:181], v[148:151], v[88:91], v[104:107]
	v_mfma_f32_16x16x32_bf16 v[184:187], v[152:155], v[88:91], v[100:103]
	v_mfma_f32_16x16x32_bf16 v[190:193], v[160:163], v[88:91], v[92:95]
	v_mfma_f32_16x16x32_bf16 v[194:197], v[168:171], v[88:91], v[84:87]
	v_mfma_f32_16x16x32_bf16 v[198:201], v[148:151], v[96:99], v[80:83]
	v_mfma_f32_16x16x32_bf16 v[204:207], v[152:155], v[96:99], v[76:79]
	v_mfma_f32_16x16x32_bf16 v[148:151], v[168:171], v[136:139], v[112:115]
	s_nop 1
	ds_read_b128 v[76:79], v183
	ds_read_b128 v[80:83], v183 offset:2048
	ds_read_b128 v[132:135], v183 offset:4096
	ds_read_b128 v[136:139], v183 offset:6144
	ds_read_b128 v[152:155], v183 offset:8192
	ds_read_b128 v[160:163], v183 offset:10240
	ds_read_b128 v[168:171], v183 offset:12288
	ds_read_b128 v[208:211], v183 offset:14336
	ds_read_b128 v[212:215], v182 offset:32768
	ds_read_b128 v[216:219], v182 offset:34816
	ds_read_b128 v[220:223], v182 offset:36864
	ds_read_b128 v[224:227], v182 offset:38912
	s_waitcnt lgkmcnt(3)
	v_mfma_f32_16x16x32_bf16 v[124:127], v[212:215], v[76:79], v[172:175]
	s_movk_i32 s0, 0xfff
	s_waitcnt lgkmcnt(2)
	v_mfma_f32_16x16x32_bf16 v[120:123], v[216:219], v[76:79], v[164:167]
	s_waitcnt lgkmcnt(1)
	v_mfma_f32_16x16x32_bf16 v[116:119], v[220:223], v[76:79], v[156:159]
	s_waitcnt lgkmcnt(0)
	v_mfma_f32_16x16x32_bf16 v[112:115], v[224:227], v[76:79], v[68:71]
	v_mfma_f32_16x16x32_bf16 v[108:111], v[212:215], v[80:83], v[140:143]
	v_mfma_f32_16x16x32_bf16 v[104:107], v[216:219], v[80:83], v[128:131]
	v_mfma_f32_16x16x32_bf16 v[100:103], v[220:223], v[80:83], v[144:147]
	v_mfma_f32_16x16x32_bf16 v[96:99], v[224:227], v[80:83], v[72:75]
	v_mfma_f32_16x16x32_bf16 v[92:95], v[212:215], v[132:135], v[178:181]
	v_mfma_f32_16x16x32_bf16 v[88:91], v[216:219], v[132:135], v[184:187]
	v_mfma_f32_16x16x32_bf16 v[84:87], v[220:223], v[132:135], v[190:193]
	v_mfma_f32_16x16x32_bf16 v[80:83], v[224:227], v[132:135], v[194:197]
	v_mov_b32_e32 v132, v188
	v_mfma_f32_16x16x32_bf16 v[76:79], v[212:215], v[136:139], v[198:201]
	v_mfma_f32_16x16x32_bf16 v[72:75], v[216:219], v[136:139], v[204:207]
	v_mfma_f32_16x16x32_bf16 v[68:71], v[220:223], v[136:139], v[64:67]
	v_mfma_f32_16x16x32_bf16 v[64:67], v[224:227], v[136:139], v[60:63]
	v_mov_b32_e32 v137, v188
	v_mfma_f32_16x16x32_bf16 v[60:63], v[212:215], v[152:155], v[56:59]
	v_and_b32_e32 v143, 15, v137
	v_and_or_b32 v136, v132, 64, s8
	v_and_b32_e32 v176, 48, v137
	v_mfma_f32_16x16x32_bf16 v[56:59], v[216:219], v[152:155], v[52:55]
	v_mfma_f32_16x16x32_bf16 v[52:55], v[220:223], v[152:155], v[48:51]
	v_mfma_f32_16x16x32_bf16 v[48:51], v[224:227], v[152:155], v[44:47]
	v_mfma_f32_16x16x32_bf16 v[44:47], v[212:215], v[160:163], v[40:43]
	v_mfma_f32_16x16x32_bf16 v[40:43], v[216:219], v[160:163], v[36:39]
	v_mfma_f32_16x16x32_bf16 v[36:39], v[224:227], v[160:163], v[28:31]
	s_nop 2
	v_and_b32_e32 v28, 0xffffff80, v132
	v_add_u32_e32 v144, s9, v28
	v_or_b32_e32 v145, v144, v143
	v_mfma_f32_16x16x32_bf16 v[28:31], v[216:219], v[168:171], v[20:23]
	v_cmp_lt_i32_e32 vcc, s0, v144
	s_mov_b32 s0, 0x2aaaaaab
	v_and_b32_e32 v142, 0x380, v144
	v_lshlrev_b32_e32 v20, 3, v145
	v_ashrrev_i32_e32 v21, 31, v20
	v_lshl_add_u64 v[128:129], v[20:21], 2, s[4:5]
	global_load_dwordx2 v[138:139], v[128:129], off offset:16
	s_nop 0
	global_load_dwordx4 v[128:131], v[128:129], off
	v_mfma_f32_16x16x32_bf16 v[20:23], v[220:223], v[168:171], v[16:19]
	v_mfma_f32_16x16x32_bf16 v[16:19], v[224:227], v[168:171], v[12:15]
	s_nop 2
	v_mul_hi_i32 v12, v136, s0
	v_lshrrev_b32_e32 v13, 31, v12
	v_lshrrev_b32_e32 v12, 5, v12
	v_add_u32_e32 v132, v12, v13
	s_movk_i32 s0, 0xc0
	v_mfma_f32_16x16x32_bf16 v[12:15], v[216:219], v[208:211], v[4:7]
	s_nop 2
	v_mul_lo_u32 v4, v132, s0
	v_sub_u32_e32 v4, v136, v4
	v_cmp_eq_u32_e64 s[0:1], s19, v4
	s_and_b64 s[40:41], s[0:1], vcc
	v_readlane_b32 s0, v255, 45
	v_mfma_f32_16x16x32_bf16 v[32:35], v[220:223], v[160:163], v[32:35]
	v_readlane_b32 s1, v255, 46
	v_mfma_f32_16x16x32_bf16 v[24:27], v[212:215], v[168:171], v[24:27]
	s_nop 0
	v_lshl_add_u64 v[134:135], s[0:1], 0, v[176:177]
	v_readlane_b32 s0, v255, 47
	v_readlane_b32 s1, v255, 48
	v_mfma_f32_16x16x32_bf16 v[8:11], v[212:215], v[208:211], v[8:11]
	s_nop 0
	v_lshl_add_u64 v[132:133], s[0:1], 0, v[176:177]
	v_mfma_f32_16x16x32_bf16 v[0:3], v[220:223], v[208:211], v[0:3]
	v_mfma_f32_16x16x32_bf16 v[4:7], v[224:227], v[208:211], v[148:151]
	s_and_saveexec_b64 s[0:1], s[40:41]
	s_cbranch_execz .LBB0_403
	v_or_b32_e32 v140, v142, v143
	v_lshlrev_b32_e32 v176, 7, v140
	v_lshl_add_u64 v[154:155], v[134:135], 0, v[176:177]
	v_lshl_add_u64 v[156:157], v[132:133], 0, v[176:177]
	global_load_dwordx4 v[146:149], v[154:155], off
	global_load_dwordx4 v[150:153], v[156:157], off
	s_waitcnt vmcnt(0)
	v_pk_mul_f32 v[158:159], v[124:125], v[150:151]
	v_pk_mul_f32 v[140:141], v[116:117], v[150:151]
	v_mul_f32_e32 v150, v126, v148
	v_mul_f32_e32 v160, v118, v152
	v_mul_f32_e32 v162, v126, v152
	v_mul_f32_e32 v148, v118, v148
	v_mov_b32_e32 v118, v127
	v_mov_b32_e32 v152, v149
	v_mov_b32_e32 v126, v119
	v_pk_mul_f32 v[164:165], v[118:119], v[152:153]
	v_pk_mul_f32 v[118:119], v[126:127], v[152:153]
	v_mov_b32_e32 v151, v164
	v_mov_b32_e32 v161, v165
	v_mov_b32_e32 v149, v118
	v_mov_b32_e32 v163, v119
	v_pk_fma_f32 v[124:125], v[124:125], v[146:147], v[140:141] neg_lo:[0,0,1] neg_hi:[0,0,1]
	v_pk_add_f32 v[140:141], v[150:151], v[160:161] neg_lo:[0,1] neg_hi:[0,1]
	v_pk_fma_f32 v[116:117], v[116:117], v[146:147], v[158:159]
	v_pk_add_f32 v[118:119], v[148:149], v[162:163]
	global_load_dwordx4 v[146:149], v[154:155], off offset:64
	global_load_dwordx4 v[150:153], v[156:157], off offset:64
	s_waitcnt vmcnt(1)
	v_mul_f32_e32 v154, v122, v148
	s_waitcnt vmcnt(0)
	v_mul_f32_e32 v156, v114, v152
	v_mul_f32_e32 v158, v122, v152
	v_mul_f32_e32 v148, v114, v148
	v_mov_b32_e32 v114, v123
	v_mov_b32_e32 v152, v149
	v_pk_mul_f32 v[160:161], v[114:115], v[152:153]
	v_mov_b32_e32 v122, v115
	v_pk_mul_f32 v[126:127], v[120:121], v[150:151]
	v_pk_mul_f32 v[150:151], v[112:113], v[150:151]
	v_mov_b32_e32 v155, v160
	v_mov_b32_e32 v157, v161
	v_pk_mul_f32 v[114:115], v[122:123], v[152:153]
	v_pk_fma_f32 v[120:121], v[120:121], v[146:147], v[150:151] neg_lo:[0,0,1] neg_hi:[0,0,1]
	v_pk_add_f32 v[150:151], v[154:155], v[156:157] neg_lo:[0,1] neg_hi:[0,1]
	v_mov_b32_e32 v149, v114
	v_mov_b32_e32 v159, v115
	v_pk_fma_f32 v[112:113], v[112:113], v[146:147], v[126:127]
	v_pk_add_f32 v[114:115], v[148:149], v[158:159]
	v_mov_b32_e32 v122, v150
	v_mov_b32_e32 v123, v151
	v_mov_b32_e32 v126, v140
	v_mov_b32_e32 v127, v141

.LBB0_422:
	s_lshl_b32 s42, s42, 1
	s_ashr_i32 s9, s9, 5
	s_sub_i32 s42, s42, s43
	s_add_i32 s9, s9, s42
	s_lshl_b32 s9, s9, 3
	s_add_i32 s9, s9, s1
	s_lshl_b32 s94, s9, 7
	s_and_b64 s[42:43], s[92:93], exec
	s_mov_b32 s1, 0x2400000
	s_cselect_b32 s1, s1, 0x2200000
	s_add_u32 s42, s36, s1
	s_addc_u32 s43, s6, 0
	s_and_b32 s95, s0, 1
	s_bitcmp1_b32 s0, 0
	s_cselect_b64 s[0:1], -1, 0
	s_cmp_eq_u32 s95, 0
	s_cbranch_scc1 .LBB0_426
	v_mov_b32_e32 v6, v188
	s_mov_b32 s95, 0x8000
	v_ashrrev_i32_e32 v7, 3, v6
	v_lshlrev_b32_e32 v4, 4, v6
	v_and_b32_e32 v176, 0x70, v4
	v_add_u32_e32 v4, s94, v7
	v_ashrrev_i32_e32 v5, 31, v4
	v_add_u32_e32 v0, s8, v7
	v_lshlrev_b64 v[4:5], 9, v[4:5]
	v_ashrrev_i32_e32 v1, 31, v0
	v_lshl_add_u64 v[4:5], s[42:43], 0, v[4:5]
	v_xor_b32_e32 v8, v7, v6
	v_lshlrev_b64 v[0:1], 9, v[0:1]
	v_lshl_add_u64 v[178:179], v[4:5], 0, v[176:177]
	v_lshlrev_b32_e32 v4, 4, v8
	v_lshl_add_u64 v[2:3], s[46:47], 0, v[0:1]
	v_and_b32_e32 v4, 0x70, v4
	v_lshl_add_u64 v[2:3], v[2:3], 0, v[176:177]
	v_lshl_or_b32 v176, v7, 7, v4
	v_lshrrev_b32_e32 v4, 4, v6
	v_and_b32_e32 v11, 7, v6
	v_bitop3_b32 v12, v4, v11, 3 bitop3:0x6c
	v_add_co_u32_e32 v4, vcc, s28, v178
	v_lshlrev_b32_e32 v8, 7, v6
	s_nop 0
	v_addc_co_u32_e32 v5, vcc, 0, v179, vcc
	v_bfe_u32 v10, v6, 4, 2
	v_add_co_u32_e32 v6, vcc, s95, v178
	s_movk_i32 s16, 0x4000
	s_nop 0
	v_addc_co_u32_e32 v7, vcc, 0, v179, vcc
	global_load_dwordx4 v[20:23], v[4:5], off
	global_load_dwordx4 v[24:27], v[6:7], off
	v_add_co_u32_e32 v4, vcc, s16, v178
	s_mov_b32 s15, 0x1c000
	s_nop 0
	v_addc_co_u32_e32 v5, vcc, 0, v179, vcc
	v_add_co_u32_e32 v6, vcc, s15, v2
	s_mov_b32 s15, 0x18000
	s_nop 0
	v_addc_co_u32_e32 v7, vcc, 0, v3, vcc
	global_load_dwordx4 v[40:43], v[4:5], off
	global_load_dwordx4 v[48:51], v[6:7], off
	v_add_co_u32_e32 v4, vcc, s15, v2
	s_mov_b32 s15, 0x14000
	s_nop 0
	v_addc_co_u32_e32 v5, vcc, 0, v3, vcc
	v_add_co_u32_e32 v6, vcc, s15, v2
	v_and_b32_e32 v9, 0xffffc780, v8
	s_nop 0
	v_addc_co_u32_e32 v7, vcc, 0, v3, vcc
	global_load_dwordx4 v[68:71], v[4:5], off
	global_load_dwordx4 v[72:75], v[6:7], off
	v_add_co_u32_e32 v4, vcc, s14, v2
	v_and_b32_e32 v8, 0x2780, v8
	s_nop 0
	v_addc_co_u32_e32 v5, vcc, 0, v3, vcc
	v_add_co_u32_e32 v6, vcc, s28, v2
	v_bitop3_b32 v10, v10, v11, 4 bitop3:0x36
	s_nop 0
	v_addc_co_u32_e32 v7, vcc, 0, v3, vcc
	global_load_dwordx4 v[84:87], v[4:5], off
	global_load_dwordx4 v[92:95], v[6:7], off
	v_add_co_u32_e32 v4, vcc, s95, v2
	v_lshl_or_b32 v0, v11, 4, v0
	s_nop 0
	v_addc_co_u32_e32 v5, vcc, 0, v3, vcc
	v_add_co_u32_e32 v6, vcc, s16, v2
	v_mov_b32_e32 v140, 0
	s_nop 0
	v_addc_co_u32_e32 v7, vcc, 0, v3, vcc
	global_load_dwordx4 v[104:107], v[4:5], off
	global_load_dwordx4 v[112:115], v[6:7], off
	global_load_dwordx4 v[56:59], v[178:179], off
	global_load_dwordx4 v[116:119], v[2:3], off
	v_lshlrev_b32_e32 v2, 4, v12
	v_or_b32_e32 v185, v9, v2
	v_or_b32_e32 v184, v8, v2
	v_lshlrev_b32_e32 v2, 4, v10
	v_or_b32_e32 v183, v9, v2
	v_or_b32_e32 v182, v8, v2
	v_lshl_add_u64 v[180:181], s[58:59], 0, v[0:1]
	s_mov_b64 s[30:31], 0
	v_mov_b32_e32 v141, v140
	v_mov_b32_e32 v142, v140
	v_mov_b32_e32 v143, v140
	v_mov_b32_e32 v0, v140
	v_mov_b32_e32 v1, v140
	v_mov_b32_e32 v2, v140
	v_mov_b32_e32 v3, v140
	v_mov_b32_e32 v4, v140
	v_mov_b32_e32 v5, v140
	v_mov_b32_e32 v6, v140
	v_mov_b32_e32 v7, v140
	v_mov_b32_e32 v8, v140
	v_mov_b32_e32 v9, v140
	v_mov_b32_e32 v10, v140
	v_mov_b32_e32 v11, v140
	v_mov_b32_e32 v12, v140
	v_mov_b32_e32 v13, v140
	v_mov_b32_e32 v14, v140
	v_mov_b32_e32 v15, v140
	v_mov_b32_e32 v16, v140
	v_mov_b32_e32 v17, v140
	v_mov_b32_e32 v18, v140
	v_mov_b32_e32 v19, v140
	v_mov_b32_e32 v28, v140
	v_mov_b32_e32 v29, v140
	v_mov_b32_e32 v30, v140
	v_mov_b32_e32 v31, v140
	v_mov_b32_e32 v32, v140
	v_mov_b32_e32 v33, v140
	v_mov_b32_e32 v34, v140
	v_mov_b32_e32 v35, v140
	v_mov_b32_e32 v36, v140
	v_mov_b32_e32 v37, v140
	v_mov_b32_e32 v38, v140
	v_mov_b32_e32 v39, v140
	v_mov_b32_e32 v44, v140
	v_mov_b32_e32 v45, v140
	v_mov_b32_e32 v46, v140
	v_mov_b32_e32 v47, v140
	v_mov_b32_e32 v52, v140
	v_mov_b32_e32 v53, v140
	v_mov_b32_e32 v54, v140
	v_mov_b32_e32 v55, v140
	v_mov_b32_e32 v60, v140
	v_mov_b32_e32 v61, v140
	v_mov_b32_e32 v62, v140
	v_mov_b32_e32 v63, v140
	v_mov_b32_e32 v64, v140
	v_mov_b32_e32 v65, v140
	v_mov_b32_e32 v66, v140
	v_mov_b32_e32 v67, v140
	v_mov_b32_e32 v76, v140
	v_mov_b32_e32 v77, v140
	v_mov_b32_e32 v78, v140
	v_mov_b32_e32 v79, v140
	v_mov_b32_e32 v80, v140
	v_mov_b32_e32 v81, v140
	v_mov_b32_e32 v82, v140
	v_mov_b32_e32 v83, v140
	v_mov_b32_e32 v88, v140
	v_mov_b32_e32 v89, v140
	v_mov_b32_e32 v90, v140
	v_mov_b32_e32 v91, v140
	v_mov_b32_e32 v96, v140
	v_mov_b32_e32 v97, v140
	v_mov_b32_e32 v98, v140
	v_mov_b32_e32 v99, v140
	v_mov_b32_e32 v100, v140
	v_mov_b32_e32 v101, v140
	v_mov_b32_e32 v102, v140
	v_mov_b32_e32 v103, v140
	v_mov_b32_e32 v108, v140
	v_mov_b32_e32 v109, v140
	v_mov_b32_e32 v110, v140
	v_mov_b32_e32 v111, v140
	v_mov_b32_e32 v120, v140
	v_mov_b32_e32 v121, v140
	v_mov_b32_e32 v122, v140
	v_mov_b32_e32 v123, v140
	v_mov_b32_e32 v124, v140
	v_mov_b32_e32 v125, v140
	v_mov_b32_e32 v126, v140
	v_mov_b32_e32 v127, v140
	v_mov_b32_e32 v128, v140
	v_mov_b32_e32 v129, v140
	v_mov_b32_e32 v130, v140
	v_mov_b32_e32 v131, v140
	v_mov_b32_e32 v132, v140
	v_mov_b32_e32 v133, v140
	v_mov_b32_e32 v134, v140
	v_mov_b32_e32 v135, v140
	v_mov_b32_e32 v136, v140
	v_mov_b32_e32 v137, v140
	v_mov_b32_e32 v138, v140
	v_mov_b32_e32 v139, v140
	v_mov_b32_e32 v144, v140
	v_mov_b32_e32 v145, v140
	v_mov_b32_e32 v146, v140
	v_mov_b32_e32 v147, v140
	v_mov_b32_e32 v148, v140
	v_mov_b32_e32 v149, v140
	v_mov_b32_e32 v150, v140
	v_mov_b32_e32 v151, v140
	v_mov_b32_e32 v152, v140
	v_mov_b32_e32 v153, v140
	v_mov_b32_e32 v154, v140
	v_mov_b32_e32 v155, v140
	v_mov_b32_e32 v156, v140
	v_mov_b32_e32 v157, v140
	v_mov_b32_e32 v158, v140
	v_mov_b32_e32 v159, v140
	v_mov_b32_e32 v160, v140
	v_mov_b32_e32 v161, v140
	v_mov_b32_e32 v162, v140
	v_mov_b32_e32 v163, v140
	v_mov_b32_e32 v164, v140
	v_mov_b32_e32 v165, v140
	v_mov_b32_e32 v166, v140
	v_mov_b32_e32 v167, v140
	v_mov_b32_e32 v168, v140
	v_mov_b32_e32 v169, v140
	v_mov_b32_e32 v170, v140
	v_mov_b32_e32 v171, v140
	v_mov_b32_e32 v172, v140
	v_mov_b32_e32 v173, v140
	v_mov_b32_e32 v174, v140
	v_mov_b32_e32 v175, v140
	s_mov_b32 s15, 0xad00000
	s_mov_b32 s17, 0xad04000
	s_mov_b32 s52, 0xad08000
	s_mov_b32 s53, 0xad0c000
	s_mov_b32 s10, 0xad10000
	s_mov_b32 s11, 0xad14000
	s_mov_b32 s12, 0xad18000
	s_mov_b32 s13, 0xad1c000
	v_readlane_b32 s98, v253, 3
	v_readlane_b32 s99, v253, 4
	v_and_b32_e32 v224, 15, v188
	v_bfe_u32 v225, v188, 4, 2
	v_lshrrev_b32_e32 v226, 2, v224
	v_sub_u32_e32 v226, 0, v226
	v_and_b32_e32 v226, 3, v226
	v_xor_b32_e32 v225, v225, v226
	v_lshlrev_b32_e32 v225, 4, v225
	v_lshl_or_b32 v225, v224, 6, v225
	v_bfe_u32 v226, v188, 7, 1
	v_lshl_or_b32 v185, v226, 13, v225
	v_bfe_u32 v226, v188, 6, 1
	v_lshl_or_b32 v184, v226, 12, v225
	v_add_u32_e32 v184, 0x4000, v184
	v_lshrrev_b32_e32 v224, 3, v188
	v_bfe_u32 v225, v188, 2, 1
	v_lshrrev_b32_e32 v226, 2, v224
	v_sub_u32_e32 v226, 0, v226
	v_and_b32_e32 v226, 3, v226
	v_and_b32_e32 v227, 3, v188
	v_xor_b32_e32 v226, v227, v226
	v_lshlrev_b32_e32 v226, 4, v226
	v_xor_b32_e32 v224, v224, v225
	v_lshl_or_b32 v226, v224, 6, v226
	v_mul_u32_u24_e32 v225, 0x6000, v225
	v_add_u32_e32 v183, v225, v226
	s_mov_b32 m0, 0
	s_sub_u32 vcc_lo, s30, s98
	v_add_u32_e32 v186, vcc_lo, v178
	v_add_u32_e32 v187, vcc_lo, v180
	s_barrier
	s_waitcnt vmcnt(0)
	ds_write_b128 v183, v[116:119]
	ds_write_b128 v183, v[112:115] offset:2048
	ds_write_b128 v183, v[104:107] offset:4096
	ds_write_b128 v183, v[92:95] offset:6144
	ds_write_b128 v183, v[84:87] offset:8192
	ds_write_b128 v183, v[72:75] offset:10240
	ds_write_b128 v183, v[68:71] offset:12288
	ds_write_b128 v183, v[48:51] offset:14336
	ds_write_b128 v183, v[56:59] offset:16384
	ds_write_b128 v183, v[40:43] offset:18432
	ds_write_b128 v183, v[24:27] offset:20480
	ds_write_b128 v183, v[20:23] offset:22528
	v_cmp_gt_u32_e32 vcc, 0x6000, v183
	v_add_u32_e32 v182, 0xc000, v183
	v_add_u32_e32 v183, 0xffffa000, v183
	s_nop 0
	v_cndmask_b32_e32 v183, v183, v182, vcc
	v_add_u32_e32 v116, s15, v187
	global_load_dwordx4 v[116:119], v116, s[98:99] offset:128
	v_add_u32_e32 v112, s17, v187
	global_load_dwordx4 v[112:115], v112, s[98:99] offset:128
	v_add_u32_e32 v104, s52, v187
	global_load_dwordx4 v[104:107], v104, s[98:99] offset:128
	v_add_u32_e32 v92, s53, v187
	global_load_dwordx4 v[92:95], v92, s[98:99] offset:128
	v_add_u32_e32 v84, s10, v187
	global_load_dwordx4 v[84:87], v84, s[98:99] offset:128
	v_add_u32_e32 v72, s11, v187
	global_load_dwordx4 v[72:75], v72, s[98:99] offset:128
	v_add_u32_e32 v68, s12, v187
	global_load_dwordx4 v[68:71], v68, s[98:99] offset:128
	v_add_u32_e32 v48, s13, v187
	global_load_dwordx4 v[48:51], v48, s[98:99] offset:128
	v_mov_b32_e32 v56, v186
	global_load_dwordx4 v[56:59], v56, s[98:99] offset:128
	v_add_u32_e32 v40, s16, v186
	global_load_dwordx4 v[40:43], v40, s[98:99] offset:128
	v_add_u32_e32 v24, s95, v186
	global_load_dwordx4 v[24:27], v24, s[98:99] offset:128
	v_add_u32_e32 v20, s28, v186
	global_load_dwordx4 v[20:23], v20, s[98:99] offset:128
	s_add_u32 s30, s30, 0x80
	s_addc_u32 s31, s31, 0
.LBB0_424:
	s_waitcnt lgkmcnt(0)
	s_barrier
	ds_read_b128 v[224:227], v184
	ds_read_b128 v[228:231], v184 offset:1024
	ds_read_b128 v[232:235], v184 offset:2048
	ds_read_b128 v[236:239], v184 offset:3072
	ds_read_b128 v[190:193], v185
	ds_read_b128 v[194:197], v185 offset:1024
	ds_read_b128 v[198:201], v185 offset:2048
	ds_read_b128 v[204:207], v185 offset:3072
	ds_read_b128 v[208:211], v185 offset:4096
	ds_read_b128 v[212:215], v185 offset:5120
	ds_read_b128 v[216:219], v185 offset:6144
	ds_read_b128 v[220:223], v185 offset:7168
	s_movk_i32 vcc_lo, 0x6000
	s_cmp_eq_u32 m0, 2
	s_cselect_b32 vcc_lo, 0xffff4000, vcc_lo
	s_add_u32 m0, m0, 1
	s_cmp_eq_u32 m0, 3
	s_cselect_b32 m0, 0, m0
	v_add_u32_e32 v185, vcc_lo, v185
	v_add_u32_e32 v184, vcc_lo, v184
	v_xor_b32_e32 v185, 64, v185
	v_xor_b32_e32 v184, 64, v184
	s_waitcnt lgkmcnt(7)
	v_mfma_f32_16x16x32_bf16 v[172:175], v[190:193], v[224:227], v[172:175]
	v_mfma_f32_16x16x32_bf16 v[168:171], v[190:193], v[228:231], v[168:171]
	v_mfma_f32_16x16x32_bf16 v[164:167], v[190:193], v[232:235], v[164:167]
	v_mfma_f32_16x16x32_bf16 v[160:163], v[190:193], v[236:239], v[160:163]
	ds_read_b128 v[190:193], v185
	s_waitcnt lgkmcnt(7)
	v_mfma_f32_16x16x32_bf16 v[156:159], v[194:197], v[224:227], v[156:159]
	v_mfma_f32_16x16x32_bf16 v[152:155], v[194:197], v[228:231], v[152:155]
	v_mfma_f32_16x16x32_bf16 v[148:151], v[194:197], v[232:235], v[148:151]
	v_mfma_f32_16x16x32_bf16 v[144:147], v[194:197], v[236:239], v[144:147]
	ds_read_b128 v[194:197], v185 offset:1024
	s_waitcnt lgkmcnt(7)
	v_mfma_f32_16x16x32_bf16 v[136:139], v[198:201], v[224:227], v[136:139]
	v_mfma_f32_16x16x32_bf16 v[132:135], v[198:201], v[228:231], v[132:135]
	v_mfma_f32_16x16x32_bf16 v[128:131], v[198:201], v[232:235], v[128:131]
	v_mfma_f32_16x16x32_bf16 v[124:127], v[198:201], v[236:239], v[124:127]
	ds_read_b128 v[198:201], v185 offset:2048
	s_waitcnt lgkmcnt(7)
	v_mfma_f32_16x16x32_bf16 v[120:123], v[204:207], v[224:227], v[120:123]
	v_mfma_f32_16x16x32_bf16 v[108:111], v[204:207], v[228:231], v[108:111]
	v_mfma_f32_16x16x32_bf16 v[100:103], v[204:207], v[232:235], v[100:103]
	v_mfma_f32_16x16x32_bf16 v[96:99], v[204:207], v[236:239], v[96:99]
	ds_read_b128 v[204:207], v185 offset:3072
	s_waitcnt lgkmcnt(7)
	v_mfma_f32_16x16x32_bf16 v[88:91], v[208:211], v[224:227], v[88:91]
	v_mfma_f32_16x16x32_bf16 v[80:83], v[208:211], v[228:231], v[80:83]
	v_mfma_f32_16x16x32_bf16 v[76:79], v[208:211], v[232:235], v[76:79]
	v_mfma_f32_16x16x32_bf16 v[64:67], v[208:211], v[236:239], v[64:67]
	ds_read_b128 v[208:211], v185 offset:4096
	s_waitcnt lgkmcnt(7)
	v_mfma_f32_16x16x32_bf16 v[60:63], v[212:215], v[224:227], v[60:63]
	v_mfma_f32_16x16x32_bf16 v[52:55], v[212:215], v[228:231], v[52:55]
	v_mfma_f32_16x16x32_bf16 v[44:47], v[212:215], v[232:235], v[44:47]
	v_mfma_f32_16x16x32_bf16 v[36:39], v[212:215], v[236:239], v[36:39]
	ds_read_b128 v[212:215], v185 offset:5120
	s_waitcnt lgkmcnt(7)
	v_mfma_f32_16x16x32_bf16 v[32:35], v[216:219], v[224:227], v[32:35]
	v_mfma_f32_16x16x32_bf16 v[28:31], v[216:219], v[228:231], v[28:31]
	v_mfma_f32_16x16x32_bf16 v[16:19], v[216:219], v[232:235], v[16:19]
	v_mfma_f32_16x16x32_bf16 v[12:15], v[216:219], v[236:239], v[12:15]
	ds_read_b128 v[216:219], v185 offset:6144
	s_waitcnt lgkmcnt(7)
	v_mfma_f32_16x16x32_bf16 v[8:11], v[220:223], v[224:227], v[8:11]
	v_mfma_f32_16x16x32_bf16 v[4:7], v[220:223], v[228:231], v[4:7]
	v_mfma_f32_16x16x32_bf16 v[0:3], v[220:223], v[232:235], v[0:3]
	v_mfma_f32_16x16x32_bf16 v[140:143], v[220:223], v[236:239], v[140:143]
	ds_read_b128 v[220:223], v185 offset:7168
	ds_read_b128 v[224:227], v184
	ds_read_b128 v[228:231], v184 offset:1024
	ds_read_b128 v[232:235], v184 offset:2048
	ds_read_b128 v[236:239], v184 offset:3072
	s_movk_i32 vcc_lo, 0x6000
	s_cmp_eq_u32 m0, 2
	s_cselect_b32 vcc_lo, 0xffff4000, vcc_lo
	s_add_u32 m0, m0, 1
	s_cmp_eq_u32 m0, 3
	s_cselect_b32 m0, 0, m0
	v_add_u32_e32 v185, vcc_lo, v185
	v_add_u32_e32 v184, vcc_lo, v184
	v_xor_b32_e32 v185, 64, v185
	v_xor_b32_e32 v184, 64, v184
	s_sub_u32 vcc_lo, s30, s98
	v_add_u32_e32 v186, vcc_lo, v178
	v_add_u32_e32 v187, vcc_lo, v180
	s_barrier
	s_waitcnt lgkmcnt(0)
	v_mfma_f32_16x16x32_bf16 v[172:175], v[190:193], v[224:227], v[172:175]
	v_mfma_f32_16x16x32_bf16 v[168:171], v[190:193], v[228:231], v[168:171]
	v_mfma_f32_16x16x32_bf16 v[164:167], v[190:193], v[232:235], v[164:167]
	v_mfma_f32_16x16x32_bf16 v[160:163], v[190:193], v[236:239], v[160:163]
	s_waitcnt vmcnt(11)
	ds_write_b128 v183, v[116:119]
	v_add_u32_e32 v116, s15, v187
	global_load_dwordx4 v[116:119], v116, s[98:99] offset:128
	s_waitcnt vmcnt(11)
	ds_write_b128 v183, v[112:115] offset:2048
	v_add_u32_e32 v112, s17, v187
	global_load_dwordx4 v[112:115], v112, s[98:99] offset:128
	v_mfma_f32_16x16x32_bf16 v[156:159], v[194:197], v[224:227], v[156:159]
	v_mfma_f32_16x16x32_bf16 v[152:155], v[194:197], v[228:231], v[152:155]
	v_mfma_f32_16x16x32_bf16 v[148:151], v[194:197], v[232:235], v[148:151]
	v_mfma_f32_16x16x32_bf16 v[144:147], v[194:197], v[236:239], v[144:147]
	s_waitcnt vmcnt(11)
	ds_write_b128 v183, v[104:107] offset:4096
	v_add_u32_e32 v104, s52, v187
	global_load_dwordx4 v[104:107], v104, s[98:99] offset:128
	v_mfma_f32_16x16x32_bf16 v[136:139], v[198:201], v[224:227], v[136:139]
	v_mfma_f32_16x16x32_bf16 v[132:135], v[198:201], v[228:231], v[132:135]
	v_mfma_f32_16x16x32_bf16 v[128:131], v[198:201], v[232:235], v[128:131]
	v_mfma_f32_16x16x32_bf16 v[124:127], v[198:201], v[236:239], v[124:127]
	s_waitcnt vmcnt(11)
	ds_write_b128 v183, v[92:95] offset:6144
	v_add_u32_e32 v92, s53, v187
	global_load_dwordx4 v[92:95], v92, s[98:99] offset:128
	s_waitcnt vmcnt(11)
	ds_write_b128 v183, v[84:87] offset:8192
	v_add_u32_e32 v84, s10, v187
	global_load_dwordx4 v[84:87], v84, s[98:99] offset:128
	v_mfma_f32_16x16x32_bf16 v[120:123], v[204:207], v[224:227], v[120:123]
	v_mfma_f32_16x16x32_bf16 v[108:111], v[204:207], v[228:231], v[108:111]
	v_mfma_f32_16x16x32_bf16 v[100:103], v[204:207], v[232:235], v[100:103]
	v_mfma_f32_16x16x32_bf16 v[96:99], v[204:207], v[236:239], v[96:99]
	s_waitcnt vmcnt(11)
	ds_write_b128 v183, v[72:75] offset:10240
	v_add_u32_e32 v72, s11, v187
	global_load_dwordx4 v[72:75], v72, s[98:99] offset:128
	v_mfma_f32_16x16x32_bf16 v[88:91], v[208:211], v[224:227], v[88:91]
	v_mfma_f32_16x16x32_bf16 v[80:83], v[208:211], v[228:231], v[80:83]
	v_mfma_f32_16x16x32_bf16 v[76:79], v[208:211], v[232:235], v[76:79]
	v_mfma_f32_16x16x32_bf16 v[64:67], v[208:211], v[236:239], v[64:67]
	s_waitcnt vmcnt(11)
	ds_write_b128 v183, v[68:71] offset:12288
	v_add_u32_e32 v68, s12, v187
	global_load_dwordx4 v[68:71], v68, s[98:99] offset:128
	s_waitcnt vmcnt(11)
	ds_write_b128 v183, v[48:51] offset:14336
	v_add_u32_e32 v48, s13, v187
	global_load_dwordx4 v[48:51], v48, s[98:99] offset:128
	v_mfma_f32_16x16x32_bf16 v[60:63], v[212:215], v[224:227], v[60:63]
	v_mfma_f32_16x16x32_bf16 v[52:55], v[212:215], v[228:231], v[52:55]
	v_mfma_f32_16x16x32_bf16 v[44:47], v[212:215], v[232:235], v[44:47]
	v_mfma_f32_16x16x32_bf16 v[36:39], v[212:215], v[236:239], v[36:39]
	s_waitcnt vmcnt(11)
	ds_write_b128 v183, v[56:59] offset:16384
	v_mov_b32_e32 v56, v186
	global_load_dwordx4 v[56:59], v56, s[98:99] offset:128
	v_mfma_f32_16x16x32_bf16 v[32:35], v[216:219], v[224:227], v[32:35]
	v_mfma_f32_16x16x32_bf16 v[28:31], v[216:219], v[228:231], v[28:31]
	v_mfma_f32_16x16x32_bf16 v[16:19], v[216:219], v[232:235], v[16:19]
	v_mfma_f32_16x16x32_bf16 v[12:15], v[216:219], v[236:239], v[12:15]
	s_waitcnt vmcnt(11)
	ds_write_b128 v183, v[40:43] offset:18432
	v_add_u32_e32 v40, s16, v186
	global_load_dwordx4 v[40:43], v40, s[98:99] offset:128
	s_waitcnt vmcnt(11)
	ds_write_b128 v183, v[24:27] offset:20480
	v_add_u32_e32 v24, s95, v186
	global_load_dwordx4 v[24:27], v24, s[98:99] offset:128
	v_mfma_f32_16x16x32_bf16 v[8:11], v[220:223], v[224:227], v[8:11]
	v_mfma_f32_16x16x32_bf16 v[4:7], v[220:223], v[228:231], v[4:7]
	v_mfma_f32_16x16x32_bf16 v[0:3], v[220:223], v[232:235], v[0:3]
	v_mfma_f32_16x16x32_bf16 v[140:143], v[220:223], v[236:239], v[140:143]
	s_waitcnt vmcnt(11)
	ds_write_b128 v183, v[20:23] offset:22528
	v_add_u32_e32 v20, s28, v186
	global_load_dwordx4 v[20:23], v20, s[98:99] offset:128
	v_cmp_gt_u32_e32 vcc, 0x6000, v183
	v_add_u32_e32 v182, 0xc000, v183
	v_add_u32_e32 v183, 0xffffa000, v183
	s_nop 0
	v_cndmask_b32_e32 v183, v183, v182, vcc
	s_add_u32 s30, s30, 0x80
	s_addc_u32 s31, s31, 0
	s_cmpk_eq_i32 s30, 0x180
	s_cbranch_scc0 .LBB0_424
	s_waitcnt lgkmcnt(0)
	s_barrier
	ds_read_b128 v[224:227], v184
	ds_read_b128 v[228:231], v184 offset:1024
	ds_read_b128 v[232:235], v184 offset:2048
	ds_read_b128 v[236:239], v184 offset:3072
	ds_read_b128 v[190:193], v185
	ds_read_b128 v[194:197], v185 offset:1024
	ds_read_b128 v[198:201], v185 offset:2048
	ds_read_b128 v[204:207], v185 offset:3072
	ds_read_b128 v[208:211], v185 offset:4096
	ds_read_b128 v[212:215], v185 offset:5120
	ds_read_b128 v[216:219], v185 offset:6144
	ds_read_b128 v[220:223], v185 offset:7168
	s_movk_i32 vcc_lo, 0x6000
	s_cmp_eq_u32 m0, 2
	s_cselect_b32 vcc_lo, 0xffff4000, vcc_lo
	s_add_u32 m0, m0, 1
	s_cmp_eq_u32 m0, 3
	s_cselect_b32 m0, 0, m0
	v_add_u32_e32 v185, vcc_lo, v185
	v_add_u32_e32 v184, vcc_lo, v184
	v_xor_b32_e32 v185, 64, v185
	v_xor_b32_e32 v184, 64, v184
	s_waitcnt lgkmcnt(7)
	v_mfma_f32_16x16x32_bf16 v[172:175], v[190:193], v[224:227], v[172:175]
	v_mfma_f32_16x16x32_bf16 v[168:171], v[190:193], v[228:231], v[168:171]
	v_mfma_f32_16x16x32_bf16 v[164:167], v[190:193], v[232:235], v[164:167]
	v_mfma_f32_16x16x32_bf16 v[160:163], v[190:193], v[236:239], v[160:163]
	ds_read_b128 v[190:193], v185
	s_waitcnt lgkmcnt(7)
	v_mfma_f32_16x16x32_bf16 v[156:159], v[194:197], v[224:227], v[156:159]
	v_mfma_f32_16x16x32_bf16 v[152:155], v[194:197], v[228:231], v[152:155]
	v_mfma_f32_16x16x32_bf16 v[148:151], v[194:197], v[232:235], v[148:151]
	v_mfma_f32_16x16x32_bf16 v[144:147], v[194:197], v[236:239], v[144:147]
	ds_read_b128 v[194:197], v185 offset:1024
	s_waitcnt lgkmcnt(7)
	v_mfma_f32_16x16x32_bf16 v[136:139], v[198:201], v[224:227], v[136:139]
	v_mfma_f32_16x16x32_bf16 v[132:135], v[198:201], v[228:231], v[132:135]
	v_mfma_f32_16x16x32_bf16 v[128:131], v[198:201], v[232:235], v[128:131]
	v_mfma_f32_16x16x32_bf16 v[124:127], v[198:201], v[236:239], v[124:127]
	ds_read_b128 v[198:201], v185 offset:2048
	s_waitcnt lgkmcnt(7)
	v_mfma_f32_16x16x32_bf16 v[120:123], v[204:207], v[224:227], v[120:123]
	v_mfma_f32_16x16x32_bf16 v[108:111], v[204:207], v[228:231], v[108:111]
	v_mfma_f32_16x16x32_bf16 v[100:103], v[204:207], v[232:235], v[100:103]
	v_mfma_f32_16x16x32_bf16 v[96:99], v[204:207], v[236:239], v[96:99]
	ds_read_b128 v[204:207], v185 offset:3072
	s_waitcnt lgkmcnt(7)
	v_mfma_f32_16x16x32_bf16 v[88:91], v[208:211], v[224:227], v[88:91]
	v_mfma_f32_16x16x32_bf16 v[80:83], v[208:211], v[228:231], v[80:83]
	v_mfma_f32_16x16x32_bf16 v[76:79], v[208:211], v[232:235], v[76:79]
	v_mfma_f32_16x16x32_bf16 v[64:67], v[208:211], v[236:239], v[64:67]
	ds_read_b128 v[208:211], v185 offset:4096
	s_waitcnt lgkmcnt(7)
	v_mfma_f32_16x16x32_bf16 v[60:63], v[212:215], v[224:227], v[60:63]
	v_mfma_f32_16x16x32_bf16 v[52:55], v[212:215], v[228:231], v[52:55]
	v_mfma_f32_16x16x32_bf16 v[44:47], v[212:215], v[232:235], v[44:47]
	v_mfma_f32_16x16x32_bf16 v[36:39], v[212:215], v[236:239], v[36:39]
	ds_read_b128 v[212:215], v185 offset:5120
	s_waitcnt lgkmcnt(7)
	v_mfma_f32_16x16x32_bf16 v[32:35], v[216:219], v[224:227], v[32:35]
	v_mfma_f32_16x16x32_bf16 v[28:31], v[216:219], v[228:231], v[28:31]
	v_mfma_f32_16x16x32_bf16 v[16:19], v[216:219], v[232:235], v[16:19]
	v_mfma_f32_16x16x32_bf16 v[12:15], v[216:219], v[236:239], v[12:15]
	ds_read_b128 v[216:219], v185 offset:6144
	s_waitcnt lgkmcnt(7)
	v_mfma_f32_16x16x32_bf16 v[8:11], v[220:223], v[224:227], v[8:11]
	v_mfma_f32_16x16x32_bf16 v[4:7], v[220:223], v[228:231], v[4:7]
	v_mfma_f32_16x16x32_bf16 v[0:3], v[220:223], v[232:235], v[0:3]
	v_mfma_f32_16x16x32_bf16 v[140:143], v[220:223], v[236:239], v[140:143]
	ds_read_b128 v[220:223], v185 offset:7168
	ds_read_b128 v[224:227], v184
	ds_read_b128 v[228:231], v184 offset:1024
	ds_read_b128 v[232:235], v184 offset:2048
	ds_read_b128 v[236:239], v184 offset:3072
	s_movk_i32 vcc_lo, 0x6000
	s_cmp_eq_u32 m0, 2
	s_cselect_b32 vcc_lo, 0xffff4000, vcc_lo
	s_add_u32 m0, m0, 1
	s_cmp_eq_u32 m0, 3
	s_cselect_b32 m0, 0, m0
	v_add_u32_e32 v185, vcc_lo, v185
	v_add_u32_e32 v184, vcc_lo, v184
	v_xor_b32_e32 v185, 64, v185
	v_xor_b32_e32 v184, 64, v184
	s_waitcnt lgkmcnt(0)
	v_mfma_f32_16x16x32_bf16 v[172:175], v[190:193], v[224:227], v[172:175]
	v_mfma_f32_16x16x32_bf16 v[168:171], v[190:193], v[228:231], v[168:171]
	v_mfma_f32_16x16x32_bf16 v[164:167], v[190:193], v[232:235], v[164:167]
	v_mfma_f32_16x16x32_bf16 v[160:163], v[190:193], v[236:239], v[160:163]
	v_mfma_f32_16x16x32_bf16 v[156:159], v[194:197], v[224:227], v[156:159]
	v_mfma_f32_16x16x32_bf16 v[152:155], v[194:197], v[228:231], v[152:155]
	v_mfma_f32_16x16x32_bf16 v[148:151], v[194:197], v[232:235], v[148:151]
	v_mfma_f32_16x16x32_bf16 v[144:147], v[194:197], v[236:239], v[144:147]
	v_mfma_f32_16x16x32_bf16 v[136:139], v[198:201], v[224:227], v[136:139]
	v_mfma_f32_16x16x32_bf16 v[132:135], v[198:201], v[228:231], v[132:135]
	v_mfma_f32_16x16x32_bf16 v[128:131], v[198:201], v[232:235], v[128:131]
	v_mfma_f32_16x16x32_bf16 v[124:127], v[198:201], v[236:239], v[124:127]
	v_mfma_f32_16x16x32_bf16 v[120:123], v[204:207], v[224:227], v[120:123]
	v_mfma_f32_16x16x32_bf16 v[108:111], v[204:207], v[228:231], v[108:111]
	v_mfma_f32_16x16x32_bf16 v[100:103], v[204:207], v[232:235], v[100:103]
	v_mfma_f32_16x16x32_bf16 v[96:99], v[204:207], v[236:239], v[96:99]
	v_mfma_f32_16x16x32_bf16 v[88:91], v[208:211], v[224:227], v[88:91]
	v_mfma_f32_16x16x32_bf16 v[80:83], v[208:211], v[228:231], v[80:83]
	v_mfma_f32_16x16x32_bf16 v[76:79], v[208:211], v[232:235], v[76:79]
	v_mfma_f32_16x16x32_bf16 v[64:67], v[208:211], v[236:239], v[64:67]
	v_mfma_f32_16x16x32_bf16 v[60:63], v[212:215], v[224:227], v[60:63]
	v_mfma_f32_16x16x32_bf16 v[52:55], v[212:215], v[228:231], v[52:55]
	v_mfma_f32_16x16x32_bf16 v[44:47], v[212:215], v[232:235], v[44:47]
	v_mfma_f32_16x16x32_bf16 v[36:39], v[212:215], v[236:239], v[36:39]
	v_mfma_f32_16x16x32_bf16 v[32:35], v[216:219], v[224:227], v[32:35]
	v_mfma_f32_16x16x32_bf16 v[28:31], v[216:219], v[228:231], v[28:31]
	v_mfma_f32_16x16x32_bf16 v[16:19], v[216:219], v[232:235], v[16:19]
	v_mfma_f32_16x16x32_bf16 v[12:15], v[216:219], v[236:239], v[12:15]
	v_mfma_f32_16x16x32_bf16 v[8:11], v[220:223], v[224:227], v[8:11]
	v_mfma_f32_16x16x32_bf16 v[4:7], v[220:223], v[228:231], v[4:7]
	v_mfma_f32_16x16x32_bf16 v[0:3], v[220:223], v[232:235], v[0:3]
	v_mfma_f32_16x16x32_bf16 v[140:143], v[220:223], v[236:239], v[140:143]
	v_lshrrev_b32_e32 v224, 4, v188
	v_and_b32_e32 v225, 7, v188
	v_bitop3_b32 v226, v224, v225, 3 bitop3:0x6c
	v_lshlrev_b32_e32 v227, 7, v188
	v_bfe_u32 v228, v188, 4, 2
	v_and_b32_e32 v229, 0xffffc780, v227
	v_and_b32_e32 v227, 0x2780, v227
	v_bitop3_b32 v228, v228, v225, 4 bitop3:0x36
	v_lshlrev_b32_e32 v226, 4, v226
	v_lshlrev_b32_e32 v228, 4, v228
	v_or_b32_e32 v185, v229, v226
	v_or_b32_e32 v184, v227, v226
	v_or_b32_e32 v183, v229, v228
	v_or_b32_e32 v182, v227, v228
	s_waitcnt vmcnt(0)
	s_barrier
	s_waitcnt vmcnt(10)
	ds_write_b128 v176, v[116:119]
	s_waitcnt vmcnt(9)
	ds_write_b128 v176, v[112:115] offset:4096
	s_waitcnt vmcnt(8)
	ds_write_b128 v176, v[104:107] offset:8192
	s_waitcnt vmcnt(7)
	ds_write_b128 v176, v[92:95] offset:12288
	s_waitcnt vmcnt(6)
	ds_write_b128 v176, v[84:87] offset:16384
	s_waitcnt vmcnt(5)
	ds_write_b128 v176, v[72:75] offset:20480
	s_waitcnt vmcnt(4)
	ds_write_b128 v176, v[68:71] offset:24576
	s_waitcnt vmcnt(3)
	ds_write_b128 v176, v[48:51] offset:28672
	ds_write_b128 v176, v[56:59] offset:32768
	s_waitcnt vmcnt(2)
	ds_write_b128 v176, v[40:43] offset:36864
	s_waitcnt vmcnt(1)
	ds_write_b128 v176, v[24:27] offset:40960
	s_waitcnt vmcnt(0)
	ds_write_b128 v176, v[20:23] offset:45056
	s_waitcnt lgkmcnt(0)
	s_barrier
	ds_read_b128 v[20:23], v185
	ds_read_b128 v[24:27], v185 offset:2048
	ds_read_b128 v[40:43], v185 offset:4096
	ds_read_b128 v[48:51], v185 offset:6144
	ds_read_b128 v[56:59], v185 offset:8192
	ds_read_b128 v[68:71], v185 offset:10240
	ds_read_b128 v[72:75], v185 offset:12288
	ds_read_b128 v[84:87], v185 offset:14336
	ds_read_b128 v[92:95], v184 offset:32768
	ds_read_b128 v[104:107], v184 offset:34816
	ds_read_b128 v[112:115], v184 offset:36864
	ds_read_b128 v[116:119], v184 offset:38912
	s_waitcnt lgkmcnt(3)
	v_mfma_f32_16x16x32_bf16 v[172:175], v[20:23], v[92:95], v[172:175]
	s_waitcnt lgkmcnt(2)
	v_mfma_f32_16x16x32_bf16 v[168:171], v[20:23], v[104:107], v[168:171]
	s_waitcnt lgkmcnt(1)
	v_mfma_f32_16x16x32_bf16 v[164:167], v[20:23], v[112:115], v[164:167]
	s_waitcnt lgkmcnt(0)
	v_mfma_f32_16x16x32_bf16 v[20:23], v[20:23], v[116:119], v[160:163]
	v_mfma_f32_16x16x32_bf16 v[156:159], v[24:27], v[92:95], v[156:159]
	v_mfma_f32_16x16x32_bf16 v[152:155], v[24:27], v[104:107], v[152:155]
	v_mfma_f32_16x16x32_bf16 v[148:151], v[24:27], v[112:115], v[148:151]
	v_mfma_f32_16x16x32_bf16 v[24:27], v[24:27], v[116:119], v[144:147]
	v_mfma_f32_16x16x32_bf16 v[136:139], v[40:43], v[92:95], v[136:139]
	v_mfma_f32_16x16x32_bf16 v[132:135], v[40:43], v[104:107], v[132:135]
	v_mfma_f32_16x16x32_bf16 v[128:131], v[40:43], v[112:115], v[128:131]
	v_mfma_f32_16x16x32_bf16 v[40:43], v[40:43], v[116:119], v[124:127]
	v_mfma_f32_16x16x32_bf16 v[144:147], v[48:51], v[92:95], v[120:123]
	v_mfma_f32_16x16x32_bf16 v[160:163], v[48:51], v[104:107], v[108:111]
	v_mfma_f32_16x16x32_bf16 v[178:181], v[48:51], v[112:115], v[100:103]
	v_mfma_f32_16x16x32_bf16 v[48:51], v[48:51], v[116:119], v[96:99]
	v_mfma_f32_16x16x32_bf16 v[16:19], v[72:75], v[112:115], v[16:19]
	v_mfma_f32_16x16x32_bf16 v[12:15], v[72:75], v[116:119], v[12:15]
	v_mfma_f32_16x16x32_bf16 v[8:11], v[84:87], v[92:95], v[8:11]
	v_mfma_f32_16x16x32_bf16 v[4:7], v[84:87], v[104:107], v[4:7]
	v_mfma_f32_16x16x32_bf16 v[0:3], v[84:87], v[112:115], v[0:3]
	v_mfma_f32_16x16x32_bf16 v[184:187], v[56:59], v[92:95], v[88:91]
	v_mfma_f32_16x16x32_bf16 v[190:193], v[56:59], v[104:107], v[80:83]
	v_mfma_f32_16x16x32_bf16 v[194:197], v[56:59], v[112:115], v[76:79]
	v_mfma_f32_16x16x32_bf16 v[56:59], v[56:59], v[116:119], v[64:67]
	v_mfma_f32_16x16x32_bf16 v[198:201], v[68:71], v[92:95], v[60:63]
	v_mfma_f32_16x16x32_bf16 v[52:55], v[68:71], v[104:107], v[52:55]
	v_mfma_f32_16x16x32_bf16 v[204:207], v[68:71], v[112:115], v[44:47]
	v_mfma_f32_16x16x32_bf16 v[208:211], v[68:71], v[116:119], v[36:39]
	v_mfma_f32_16x16x32_bf16 v[212:215], v[72:75], v[92:95], v[32:35]
	v_mfma_f32_16x16x32_bf16 v[216:219], v[72:75], v[104:107], v[28:31]
	v_mfma_f32_16x16x32_bf16 v[140:143], v[84:87], v[116:119], v[140:143]
	s_nop 1
	ds_read_b128 v[28:31], v183
	ds_read_b128 v[32:35], v183 offset:2048
	ds_read_b128 v[36:39], v183 offset:4096
	ds_read_b128 v[44:47], v183 offset:6144
	ds_read_b128 v[220:223], v183 offset:8192
	ds_read_b128 v[224:227], v183 offset:10240
	ds_read_b128 v[228:231], v183 offset:12288
	ds_read_b128 v[232:235], v183 offset:14336
	ds_read_b128 v[236:239], v182 offset:32768
	ds_read_b128 v[240:243], v182 offset:34816
	ds_read_b128 v[244:247], v182 offset:36864
	ds_read_b128 v[248:251], v182 offset:38912
	s_waitcnt lgkmcnt(3)
	v_mfma_f32_16x16x32_bf16 v[124:127], v[28:31], v[236:239], v[172:175]
	v_readlane_b32 s16, v255, 27
	s_mov_b64 s[30:31], 0
	v_readlane_b32 s17, v255, 28
	s_waitcnt lgkmcnt(2)
	v_mfma_f32_16x16x32_bf16 v[120:123], v[28:31], v[240:243], v[168:171]
	v_readlane_b32 s11, v255, 16
	v_readlane_b32 s10, v255, 18
	s_waitcnt lgkmcnt(1)
	v_mfma_f32_16x16x32_bf16 v[116:119], v[28:31], v[244:247], v[164:167]
	s_waitcnt lgkmcnt(0)
	v_mfma_f32_16x16x32_bf16 v[112:115], v[28:31], v[248:251], v[20:23]
	v_mfma_f32_16x16x32_bf16 v[108:111], v[32:35], v[236:239], v[156:159]
	v_mfma_f32_16x16x32_bf16 v[104:107], v[32:35], v[240:243], v[152:155]
	v_mfma_f32_16x16x32_bf16 v[100:103], v[32:35], v[244:247], v[148:151]
	v_mfma_f32_16x16x32_bf16 v[96:99], v[32:35], v[248:251], v[24:27]
	v_mfma_f32_16x16x32_bf16 v[92:95], v[36:39], v[236:239], v[136:139]
	v_mfma_f32_16x16x32_bf16 v[88:91], v[36:39], v[240:243], v[132:135]
	v_mfma_f32_16x16x32_bf16 v[84:87], v[36:39], v[244:247], v[128:131]
	v_mfma_f32_16x16x32_bf16 v[80:83], v[36:39], v[248:251], v[40:43]
	v_mfma_f32_16x16x32_bf16 v[76:79], v[44:47], v[236:239], v[144:147]
	v_mfma_f32_16x16x32_bf16 v[72:75], v[44:47], v[240:243], v[160:163]
	v_mfma_f32_16x16x32_bf16 v[68:71], v[44:47], v[244:247], v[178:181]
	v_mfma_f32_16x16x32_bf16 v[64:67], v[44:47], v[248:251], v[48:51]
	v_mfma_f32_16x16x32_bf16 v[60:63], v[220:223], v[236:239], v[184:187]
	v_mfma_f32_16x16x32_bf16 v[156:159], v[220:223], v[240:243], v[190:193]
	v_mfma_f32_16x16x32_bf16 v[152:155], v[220:223], v[244:247], v[194:197]
	v_mfma_f32_16x16x32_bf16 v[48:51], v[220:223], v[248:251], v[56:59]
	v_mfma_f32_16x16x32_bf16 v[44:47], v[224:227], v[236:239], v[198:201]
	v_mfma_f32_16x16x32_bf16 v[40:43], v[224:227], v[240:243], v[52:55]
	v_mfma_f32_16x16x32_bf16 v[36:39], v[224:227], v[244:247], v[204:207]
	v_mfma_f32_16x16x32_bf16 v[32:35], v[224:227], v[248:251], v[208:211]
	v_mfma_f32_16x16x32_bf16 v[28:31], v[228:231], v[236:239], v[212:215]
	v_mfma_f32_16x16x32_bf16 v[24:27], v[228:231], v[240:243], v[216:219]
	v_mfma_f32_16x16x32_bf16 v[20:23], v[228:231], v[244:247], v[16:19]
	v_mfma_f32_16x16x32_bf16 v[16:19], v[228:231], v[248:251], v[12:15]
	v_mfma_f32_16x16x32_bf16 v[12:15], v[232:235], v[236:239], v[8:11]
	v_mfma_f32_16x16x32_bf16 v[8:11], v[232:235], v[240:243], v[4:7]
	v_xor_b32_e32 v240, 32, v203
	v_mfma_f32_16x16x32_bf16 v[0:3], v[232:235], v[244:247], v[0:3]
	v_mfma_f32_16x16x32_bf16 v[4:7], v[232:235], v[248:251], v[140:143]
.LBB0_426:
	s_and_b64 vcc, exec, s[30:31]
	s_cbranch_vccz .LBB0_430
	s_nop 5
	v_mov_b32_e32 v6, v188
	s_mov_b32 s15, 0x1c000
	v_ashrrev_i32_e32 v7, 3, v6
	v_lshlrev_b32_e32 v4, 4, v6
	v_and_b32_e32 v176, 0x70, v4
	v_add_u32_e32 v4, s94, v7
	v_ashrrev_i32_e32 v5, 31, v4
	v_add_u32_e32 v0, s8, v7
	v_lshlrev_b64 v[4:5], 9, v[4:5]
	v_ashrrev_i32_e32 v1, 31, v0
	v_lshl_add_u64 v[4:5], s[42:43], 0, v[4:5]
	v_xor_b32_e32 v8, v7, v6
	v_lshlrev_b64 v[0:1], 9, v[0:1]
	v_lshl_add_u64 v[178:179], v[4:5], 0, v[176:177]
	v_lshlrev_b32_e32 v4, 4, v8
	v_lshl_add_u64 v[2:3], s[46:47], 0, v[0:1]
	v_and_b32_e32 v4, 0x70, v4
	v_lshl_add_u64 v[2:3], v[2:3], 0, v[176:177]
	v_lshl_or_b32 v176, v7, 7, v4
	v_lshrrev_b32_e32 v4, 4, v6
	v_and_b32_e32 v11, 7, v6
	v_bitop3_b32 v12, v4, v11, 3 bitop3:0x6c
	v_add_co_u32_e32 v4, vcc, s28, v178
	s_mov_b32 s42, 0x8000
	s_nop 0
	v_addc_co_u32_e32 v5, vcc, 0, v179, vcc
	v_lshlrev_b32_e32 v8, 7, v6
	v_bfe_u32 v10, v6, 4, 2
	v_add_co_u32_e32 v6, vcc, s42, v178
	s_movk_i32 s43, 0x4000
	s_nop 0
	v_addc_co_u32_e32 v7, vcc, 0, v179, vcc
	global_load_dwordx4 v[20:23], v[4:5], off
	global_load_dwordx4 v[24:27], v[6:7], off
	v_add_co_u32_e32 v4, vcc, s43, v178
	v_and_b32_e32 v9, 0xffffc780, v8
	s_nop 0
	v_addc_co_u32_e32 v5, vcc, 0, v179, vcc
	v_add_co_u32_e32 v6, vcc, s15, v2
	s_mov_b32 s15, 0x18000
	s_nop 0
	v_addc_co_u32_e32 v7, vcc, 0, v3, vcc
	global_load_dwordx4 v[40:43], v[4:5], off
	global_load_dwordx4 v[48:51], v[6:7], off
	v_add_co_u32_e32 v4, vcc, s15, v2
	s_mov_b32 s15, 0x14000
	s_nop 0
	v_addc_co_u32_e32 v5, vcc, 0, v3, vcc
	v_add_co_u32_e32 v6, vcc, s15, v2
	v_and_b32_e32 v8, 0x2780, v8
	s_nop 0
	v_addc_co_u32_e32 v7, vcc, 0, v3, vcc
	global_load_dwordx4 v[68:71], v[4:5], off
	global_load_dwordx4 v[72:75], v[6:7], off
	v_add_co_u32_e32 v4, vcc, s14, v2
	v_bitop3_b32 v10, v10, v11, 4 bitop3:0x36
	s_nop 0
	v_addc_co_u32_e32 v5, vcc, 0, v3, vcc
	v_add_co_u32_e32 v6, vcc, s28, v2
	v_lshl_or_b32 v0, v11, 4, v0
	s_nop 0
	v_addc_co_u32_e32 v7, vcc, 0, v3, vcc
	global_load_dwordx4 v[84:87], v[4:5], off
	global_load_dwordx4 v[92:95], v[6:7], off
	v_add_co_u32_e32 v4, vcc, s42, v2
	v_mov_b32_e32 v140, 0
	s_nop 0
	v_addc_co_u32_e32 v5, vcc, 0, v3, vcc
	v_add_co_u32_e32 v6, vcc, s43, v2
	v_lshl_add_u64 v[180:181], s[58:59], 0, v[0:1]
	s_nop 0
	v_addc_co_u32_e32 v7, vcc, 0, v3, vcc
	global_load_dwordx4 v[104:107], v[4:5], off
	global_load_dwordx4 v[112:115], v[6:7], off
	global_load_dwordx4 v[56:59], v[178:179], off
	global_load_dwordx4 v[116:119], v[2:3], off
	v_lshlrev_b32_e32 v2, 4, v12
	v_or_b32_e32 v185, v9, v2
	v_or_b32_e32 v184, v8, v2
	v_lshlrev_b32_e32 v2, 4, v10
	v_or_b32_e32 v183, v9, v2
	v_or_b32_e32 v182, v8, v2
	s_mov_b64 s[30:31], 0
	v_mov_b32_e32 v141, v140
	v_mov_b32_e32 v142, v140
	v_mov_b32_e32 v143, v140
	v_mov_b32_e32 v0, v140
	v_mov_b32_e32 v1, v140
	v_mov_b32_e32 v2, v140
	v_mov_b32_e32 v3, v140
	v_mov_b32_e32 v4, v140
	v_mov_b32_e32 v5, v140
	v_mov_b32_e32 v6, v140
	v_mov_b32_e32 v7, v140
	v_mov_b32_e32 v8, v140
	v_mov_b32_e32 v9, v140
	v_mov_b32_e32 v10, v140
	v_mov_b32_e32 v11, v140
	v_mov_b32_e32 v12, v140
	v_mov_b32_e32 v13, v140
	v_mov_b32_e32 v14, v140
	v_mov_b32_e32 v15, v140
	v_mov_b32_e32 v16, v140
	v_mov_b32_e32 v17, v140
	v_mov_b32_e32 v18, v140
	v_mov_b32_e32 v19, v140
	v_mov_b32_e32 v28, v140
	v_mov_b32_e32 v29, v140
	v_mov_b32_e32 v30, v140
	v_mov_b32_e32 v31, v140
	v_mov_b32_e32 v32, v140
	v_mov_b32_e32 v33, v140
	v_mov_b32_e32 v34, v140
	v_mov_b32_e32 v35, v140
	v_mov_b32_e32 v36, v140
	v_mov_b32_e32 v37, v140
	v_mov_b32_e32 v38, v140
	v_mov_b32_e32 v39, v140
	v_mov_b32_e32 v44, v140
	v_mov_b32_e32 v45, v140
	v_mov_b32_e32 v46, v140
	v_mov_b32_e32 v47, v140
	v_mov_b32_e32 v52, v140
	v_mov_b32_e32 v53, v140
	v_mov_b32_e32 v54, v140
	v_mov_b32_e32 v55, v140
	v_mov_b32_e32 v60, v140
	v_mov_b32_e32 v61, v140
	v_mov_b32_e32 v62, v140
	v_mov_b32_e32 v63, v140
	v_mov_b32_e32 v64, v140
	v_mov_b32_e32 v65, v140
	v_mov_b32_e32 v66, v140
	v_mov_b32_e32 v67, v140
	v_mov_b32_e32 v76, v140
	v_mov_b32_e32 v77, v140
	v_mov_b32_e32 v78, v140
	v_mov_b32_e32 v79, v140
	v_mov_b32_e32 v80, v140
	v_mov_b32_e32 v81, v140
	v_mov_b32_e32 v82, v140
	v_mov_b32_e32 v83, v140
	v_mov_b32_e32 v88, v140
	v_mov_b32_e32 v89, v140
	v_mov_b32_e32 v90, v140
	v_mov_b32_e32 v91, v140
	v_mov_b32_e32 v96, v140
	v_mov_b32_e32 v97, v140
	v_mov_b32_e32 v98, v140
	v_mov_b32_e32 v99, v140
	v_mov_b32_e32 v100, v140
	v_mov_b32_e32 v101, v140
	v_mov_b32_e32 v102, v140
	v_mov_b32_e32 v103, v140
	v_mov_b32_e32 v108, v140
	v_mov_b32_e32 v109, v140
	v_mov_b32_e32 v110, v140
	v_mov_b32_e32 v111, v140
	v_mov_b32_e32 v120, v140
	v_mov_b32_e32 v121, v140
	v_mov_b32_e32 v122, v140
	v_mov_b32_e32 v123, v140
	v_mov_b32_e32 v124, v140
	v_mov_b32_e32 v125, v140
	v_mov_b32_e32 v126, v140
	v_mov_b32_e32 v127, v140
	v_mov_b32_e32 v128, v140
	v_mov_b32_e32 v129, v140
	v_mov_b32_e32 v130, v140
	v_mov_b32_e32 v131, v140
	v_mov_b32_e32 v132, v140
	v_mov_b32_e32 v133, v140
	v_mov_b32_e32 v134, v140
	v_mov_b32_e32 v135, v140
	v_mov_b32_e32 v136, v140
	v_mov_b32_e32 v137, v140
	v_mov_b32_e32 v138, v140
	v_mov_b32_e32 v139, v140
	v_mov_b32_e32 v144, v140
	v_mov_b32_e32 v145, v140
	v_mov_b32_e32 v146, v140
	v_mov_b32_e32 v147, v140
	v_mov_b32_e32 v148, v140
	v_mov_b32_e32 v149, v140
	v_mov_b32_e32 v150, v140
	v_mov_b32_e32 v151, v140
	v_mov_b32_e32 v152, v140
	v_mov_b32_e32 v153, v140
	v_mov_b32_e32 v154, v140
	v_mov_b32_e32 v155, v140
	v_mov_b32_e32 v156, v140
	v_mov_b32_e32 v157, v140
	v_mov_b32_e32 v158, v140
	v_mov_b32_e32 v159, v140
	v_mov_b32_e32 v160, v140
	v_mov_b32_e32 v161, v140
	v_mov_b32_e32 v162, v140
	v_mov_b32_e32 v163, v140
	v_mov_b32_e32 v164, v140
	v_mov_b32_e32 v165, v140
	v_mov_b32_e32 v166, v140
	v_mov_b32_e32 v167, v140
	v_mov_b32_e32 v168, v140
	v_mov_b32_e32 v169, v140
	v_mov_b32_e32 v170, v140
	v_mov_b32_e32 v171, v140
	v_mov_b32_e32 v172, v140
	v_mov_b32_e32 v173, v140
	v_mov_b32_e32 v174, v140
	v_mov_b32_e32 v175, v140
	s_mov_b32 s14, 0xad00000
	s_mov_b32 s15, 0xad04000
	s_mov_b32 s16, 0xad08000
	s_mov_b32 s17, 0xad0c000
	s_mov_b32 s10, 0xad10000
	s_mov_b32 s11, 0xad14000
	s_mov_b32 s12, 0xad18000
	s_mov_b32 s13, 0xad1c000
	v_readlane_b32 s98, v253, 3
	v_readlane_b32 s99, v253, 4
	v_and_b32_e32 v224, 15, v188
	v_bfe_u32 v225, v188, 4, 2
	v_lshrrev_b32_e32 v226, 2, v224
	v_sub_u32_e32 v226, 0, v226
	v_and_b32_e32 v226, 3, v226
	v_xor_b32_e32 v225, v225, v226
	v_lshlrev_b32_e32 v225, 4, v225
	v_lshl_or_b32 v225, v224, 6, v225
	v_bfe_u32 v226, v188, 7, 1
	v_lshl_or_b32 v185, v226, 13, v225
	v_bfe_u32 v226, v188, 6, 1
	v_lshl_or_b32 v184, v226, 12, v225
	v_add_u32_e32 v184, 0x4000, v184
	v_lshrrev_b32_e32 v224, 3, v188
	v_bfe_u32 v225, v188, 2, 1
	v_lshrrev_b32_e32 v226, 2, v224
	v_sub_u32_e32 v226, 0, v226
	v_and_b32_e32 v226, 3, v226
	v_and_b32_e32 v227, 3, v188
	v_xor_b32_e32 v226, v227, v226
	v_lshlrev_b32_e32 v226, 4, v226
	v_xor_b32_e32 v224, v224, v225
	v_lshl_or_b32 v226, v224, 6, v226
	v_mul_u32_u24_e32 v225, 0x6000, v225
	v_add_u32_e32 v183, v225, v226
	s_mov_b32 m0, 0
	s_sub_u32 vcc_lo, s30, s98
	v_add_u32_e32 v186, vcc_lo, v178
	v_add_u32_e32 v187, vcc_lo, v180
	s_barrier
	s_waitcnt vmcnt(0)
	ds_write_b128 v183, v[116:119]
	ds_write_b128 v183, v[112:115] offset:2048
	ds_write_b128 v183, v[104:107] offset:4096
	ds_write_b128 v183, v[92:95] offset:6144
	ds_write_b128 v183, v[84:87] offset:8192
	ds_write_b128 v183, v[72:75] offset:10240
	ds_write_b128 v183, v[68:71] offset:12288
	ds_write_b128 v183, v[48:51] offset:14336
	ds_write_b128 v183, v[56:59] offset:16384
	ds_write_b128 v183, v[40:43] offset:18432
	ds_write_b128 v183, v[24:27] offset:20480
	ds_write_b128 v183, v[20:23] offset:22528
	v_cmp_gt_u32_e32 vcc, 0x6000, v183
	v_add_u32_e32 v182, 0xc000, v183
	v_add_u32_e32 v183, 0xffffa000, v183
	s_nop 0
	v_cndmask_b32_e32 v183, v183, v182, vcc
	v_add_u32_e32 v116, s14, v187
	global_load_dwordx4 v[116:119], v116, s[98:99] offset:128
	v_add_u32_e32 v112, s15, v187
	global_load_dwordx4 v[112:115], v112, s[98:99] offset:128
	v_add_u32_e32 v104, s16, v187
	global_load_dwordx4 v[104:107], v104, s[98:99] offset:128
	v_add_u32_e32 v92, s17, v187
	global_load_dwordx4 v[92:95], v92, s[98:99] offset:128
	v_add_u32_e32 v84, s10, v187
	global_load_dwordx4 v[84:87], v84, s[98:99] offset:128
	v_add_u32_e32 v72, s11, v187
	global_load_dwordx4 v[72:75], v72, s[98:99] offset:128
	v_add_u32_e32 v68, s12, v187
	global_load_dwordx4 v[68:71], v68, s[98:99] offset:128
	v_add_u32_e32 v48, s13, v187
	global_load_dwordx4 v[48:51], v48, s[98:99] offset:128
	v_mov_b32_e32 v56, v186
	global_load_dwordx4 v[56:59], v56, s[98:99] offset:128
	v_add_u32_e32 v40, s43, v186
	global_load_dwordx4 v[40:43], v40, s[98:99] offset:128
	v_add_u32_e32 v24, s42, v186
	global_load_dwordx4 v[24:27], v24, s[98:99] offset:128
	v_add_u32_e32 v20, s28, v186
	global_load_dwordx4 v[20:23], v20, s[98:99] offset:128
	s_add_u32 s30, s30, 0x80
	s_addc_u32 s31, s31, 0
.LBB0_428:
	s_waitcnt lgkmcnt(0)
	s_barrier
	ds_read_b128 v[224:227], v184
	ds_read_b128 v[228:231], v184 offset:1024
	ds_read_b128 v[232:235], v184 offset:2048
	ds_read_b128 v[236:239], v184 offset:3072
	ds_read_b128 v[190:193], v185
	ds_read_b128 v[194:197], v185 offset:1024
	ds_read_b128 v[198:201], v185 offset:2048
	ds_read_b128 v[204:207], v185 offset:3072
	ds_read_b128 v[208:211], v185 offset:4096
	ds_read_b128 v[212:215], v185 offset:5120
	ds_read_b128 v[216:219], v185 offset:6144
	ds_read_b128 v[220:223], v185 offset:7168
	s_movk_i32 vcc_lo, 0x6000
	s_cmp_eq_u32 m0, 2
	s_cselect_b32 vcc_lo, 0xffff4000, vcc_lo
	s_add_u32 m0, m0, 1
	s_cmp_eq_u32 m0, 3
	s_cselect_b32 m0, 0, m0
	v_add_u32_e32 v185, vcc_lo, v185
	v_add_u32_e32 v184, vcc_lo, v184
	v_xor_b32_e32 v185, 64, v185
	v_xor_b32_e32 v184, 64, v184
	s_waitcnt lgkmcnt(7)
	v_mfma_f32_16x16x32_bf16 v[172:175], v[224:227], v[190:193], v[172:175]
	v_mfma_f32_16x16x32_bf16 v[168:171], v[228:231], v[190:193], v[168:171]
	v_mfma_f32_16x16x32_bf16 v[164:167], v[232:235], v[190:193], v[164:167]
	v_mfma_f32_16x16x32_bf16 v[160:163], v[236:239], v[190:193], v[160:163]
	ds_read_b128 v[190:193], v185
	s_waitcnt lgkmcnt(7)
	v_mfma_f32_16x16x32_bf16 v[156:159], v[224:227], v[194:197], v[156:159]
	v_mfma_f32_16x16x32_bf16 v[152:155], v[228:231], v[194:197], v[152:155]
	v_mfma_f32_16x16x32_bf16 v[148:151], v[232:235], v[194:197], v[148:151]
	v_mfma_f32_16x16x32_bf16 v[144:147], v[236:239], v[194:197], v[144:147]
	ds_read_b128 v[194:197], v185 offset:1024
	s_waitcnt lgkmcnt(7)
	v_mfma_f32_16x16x32_bf16 v[136:139], v[224:227], v[198:201], v[136:139]
	v_mfma_f32_16x16x32_bf16 v[132:135], v[228:231], v[198:201], v[132:135]
	v_mfma_f32_16x16x32_bf16 v[128:131], v[232:235], v[198:201], v[128:131]
	v_mfma_f32_16x16x32_bf16 v[124:127], v[236:239], v[198:201], v[124:127]
	ds_read_b128 v[198:201], v185 offset:2048
	s_waitcnt lgkmcnt(7)
	v_mfma_f32_16x16x32_bf16 v[120:123], v[224:227], v[204:207], v[120:123]
	v_mfma_f32_16x16x32_bf16 v[108:111], v[228:231], v[204:207], v[108:111]
	v_mfma_f32_16x16x32_bf16 v[100:103], v[232:235], v[204:207], v[100:103]
	v_mfma_f32_16x16x32_bf16 v[96:99], v[236:239], v[204:207], v[96:99]
	ds_read_b128 v[204:207], v185 offset:3072
	s_waitcnt lgkmcnt(7)
	v_mfma_f32_16x16x32_bf16 v[88:91], v[224:227], v[208:211], v[88:91]
	v_mfma_f32_16x16x32_bf16 v[80:83], v[228:231], v[208:211], v[80:83]
	v_mfma_f32_16x16x32_bf16 v[76:79], v[232:235], v[208:211], v[76:79]
	v_mfma_f32_16x16x32_bf16 v[64:67], v[236:239], v[208:211], v[64:67]
	ds_read_b128 v[208:211], v185 offset:4096
	s_waitcnt lgkmcnt(7)
	v_mfma_f32_16x16x32_bf16 v[60:63], v[224:227], v[212:215], v[60:63]
	v_mfma_f32_16x16x32_bf16 v[52:55], v[228:231], v[212:215], v[52:55]
	v_mfma_f32_16x16x32_bf16 v[44:47], v[232:235], v[212:215], v[44:47]
	v_mfma_f32_16x16x32_bf16 v[36:39], v[236:239], v[212:215], v[36:39]
	ds_read_b128 v[212:215], v185 offset:5120
	s_waitcnt lgkmcnt(7)
	v_mfma_f32_16x16x32_bf16 v[32:35], v[224:227], v[216:219], v[32:35]
	v_mfma_f32_16x16x32_bf16 v[28:31], v[228:231], v[216:219], v[28:31]
	v_mfma_f32_16x16x32_bf16 v[16:19], v[232:235], v[216:219], v[16:19]
	v_mfma_f32_16x16x32_bf16 v[12:15], v[236:239], v[216:219], v[12:15]
	ds_read_b128 v[216:219], v185 offset:6144
	s_waitcnt lgkmcnt(7)
	v_mfma_f32_16x16x32_bf16 v[8:11], v[224:227], v[220:223], v[8:11]
	v_mfma_f32_16x16x32_bf16 v[4:7], v[228:231], v[220:223], v[4:7]
	v_mfma_f32_16x16x32_bf16 v[0:3], v[232:235], v[220:223], v[0:3]
	v_mfma_f32_16x16x32_bf16 v[140:143], v[236:239], v[220:223], v[140:143]
	ds_read_b128 v[220:223], v185 offset:7168
	ds_read_b128 v[224:227], v184
	ds_read_b128 v[228:231], v184 offset:1024
	ds_read_b128 v[232:235], v184 offset:2048
	ds_read_b128 v[236:239], v184 offset:3072
	s_movk_i32 vcc_lo, 0x6000
	s_cmp_eq_u32 m0, 2
	s_cselect_b32 vcc_lo, 0xffff4000, vcc_lo
	s_add_u32 m0, m0, 1
	s_cmp_eq_u32 m0, 3
	s_cselect_b32 m0, 0, m0
	v_add_u32_e32 v185, vcc_lo, v185
	v_add_u32_e32 v184, vcc_lo, v184
	v_xor_b32_e32 v185, 64, v185
	v_xor_b32_e32 v184, 64, v184
	s_sub_u32 vcc_lo, s30, s98
	v_add_u32_e32 v186, vcc_lo, v178
	v_add_u32_e32 v187, vcc_lo, v180
	s_barrier
	s_waitcnt lgkmcnt(0)
	v_mfma_f32_16x16x32_bf16 v[172:175], v[224:227], v[190:193], v[172:175]
	v_mfma_f32_16x16x32_bf16 v[168:171], v[228:231], v[190:193], v[168:171]
	v_mfma_f32_16x16x32_bf16 v[164:167], v[232:235], v[190:193], v[164:167]
	v_mfma_f32_16x16x32_bf16 v[160:163], v[236:239], v[190:193], v[160:163]
	s_waitcnt vmcnt(11)
	ds_write_b128 v183, v[116:119]
	v_add_u32_e32 v116, s14, v187
	global_load_dwordx4 v[116:119], v116, s[98:99] offset:128
	s_waitcnt vmcnt(11)
	ds_write_b128 v183, v[112:115] offset:2048
	v_add_u32_e32 v112, s15, v187
	global_load_dwordx4 v[112:115], v112, s[98:99] offset:128
	v_mfma_f32_16x16x32_bf16 v[156:159], v[224:227], v[194:197], v[156:159]
	v_mfma_f32_16x16x32_bf16 v[152:155], v[228:231], v[194:197], v[152:155]
	v_mfma_f32_16x16x32_bf16 v[148:151], v[232:235], v[194:197], v[148:151]
	v_mfma_f32_16x16x32_bf16 v[144:147], v[236:239], v[194:197], v[144:147]
	s_waitcnt vmcnt(11)
	ds_write_b128 v183, v[104:107] offset:4096
	v_add_u32_e32 v104, s16, v187
	global_load_dwordx4 v[104:107], v104, s[98:99] offset:128
	v_mfma_f32_16x16x32_bf16 v[136:139], v[224:227], v[198:201], v[136:139]
	v_mfma_f32_16x16x32_bf16 v[132:135], v[228:231], v[198:201], v[132:135]
	v_mfma_f32_16x16x32_bf16 v[128:131], v[232:235], v[198:201], v[128:131]
	v_mfma_f32_16x16x32_bf16 v[124:127], v[236:239], v[198:201], v[124:127]
	s_waitcnt vmcnt(11)
	ds_write_b128 v183, v[92:95] offset:6144
	v_add_u32_e32 v92, s17, v187
	global_load_dwordx4 v[92:95], v92, s[98:99] offset:128
	s_waitcnt vmcnt(11)
	ds_write_b128 v183, v[84:87] offset:8192
	v_add_u32_e32 v84, s10, v187
	global_load_dwordx4 v[84:87], v84, s[98:99] offset:128
	v_mfma_f32_16x16x32_bf16 v[120:123], v[224:227], v[204:207], v[120:123]
	v_mfma_f32_16x16x32_bf16 v[108:111], v[228:231], v[204:207], v[108:111]
	v_mfma_f32_16x16x32_bf16 v[100:103], v[232:235], v[204:207], v[100:103]
	v_mfma_f32_16x16x32_bf16 v[96:99], v[236:239], v[204:207], v[96:99]
	s_waitcnt vmcnt(11)
	ds_write_b128 v183, v[72:75] offset:10240
	v_add_u32_e32 v72, s11, v187
	global_load_dwordx4 v[72:75], v72, s[98:99] offset:128
	v_mfma_f32_16x16x32_bf16 v[88:91], v[224:227], v[208:211], v[88:91]
	v_mfma_f32_16x16x32_bf16 v[80:83], v[228:231], v[208:211], v[80:83]
	v_mfma_f32_16x16x32_bf16 v[76:79], v[232:235], v[208:211], v[76:79]
	v_mfma_f32_16x16x32_bf16 v[64:67], v[236:239], v[208:211], v[64:67]
	s_waitcnt vmcnt(11)
	ds_write_b128 v183, v[68:71] offset:12288
	v_add_u32_e32 v68, s12, v187
	global_load_dwordx4 v[68:71], v68, s[98:99] offset:128
	s_waitcnt vmcnt(11)
	ds_write_b128 v183, v[48:51] offset:14336
	v_add_u32_e32 v48, s13, v187
	global_load_dwordx4 v[48:51], v48, s[98:99] offset:128
	v_mfma_f32_16x16x32_bf16 v[60:63], v[224:227], v[212:215], v[60:63]
	v_mfma_f32_16x16x32_bf16 v[52:55], v[228:231], v[212:215], v[52:55]
	v_mfma_f32_16x16x32_bf16 v[44:47], v[232:235], v[212:215], v[44:47]
	v_mfma_f32_16x16x32_bf16 v[36:39], v[236:239], v[212:215], v[36:39]
	s_waitcnt vmcnt(11)
	ds_write_b128 v183, v[56:59] offset:16384
	v_mov_b32_e32 v56, v186
	global_load_dwordx4 v[56:59], v56, s[98:99] offset:128
	v_mfma_f32_16x16x32_bf16 v[32:35], v[224:227], v[216:219], v[32:35]
	v_mfma_f32_16x16x32_bf16 v[28:31], v[228:231], v[216:219], v[28:31]
	v_mfma_f32_16x16x32_bf16 v[16:19], v[232:235], v[216:219], v[16:19]
	v_mfma_f32_16x16x32_bf16 v[12:15], v[236:239], v[216:219], v[12:15]
	s_waitcnt vmcnt(11)
	ds_write_b128 v183, v[40:43] offset:18432
	v_add_u32_e32 v40, s43, v186
	global_load_dwordx4 v[40:43], v40, s[98:99] offset:128
	s_waitcnt vmcnt(11)
	ds_write_b128 v183, v[24:27] offset:20480
	v_add_u32_e32 v24, s42, v186
	global_load_dwordx4 v[24:27], v24, s[98:99] offset:128
	v_mfma_f32_16x16x32_bf16 v[8:11], v[224:227], v[220:223], v[8:11]
	v_mfma_f32_16x16x32_bf16 v[4:7], v[228:231], v[220:223], v[4:7]
	v_mfma_f32_16x16x32_bf16 v[0:3], v[232:235], v[220:223], v[0:3]
	v_mfma_f32_16x16x32_bf16 v[140:143], v[236:239], v[220:223], v[140:143]
	s_waitcnt vmcnt(11)
	ds_write_b128 v183, v[20:23] offset:22528
	v_add_u32_e32 v20, s28, v186
	global_load_dwordx4 v[20:23], v20, s[98:99] offset:128
	v_cmp_gt_u32_e32 vcc, 0x6000, v183
	v_add_u32_e32 v182, 0xc000, v183
	v_add_u32_e32 v183, 0xffffa000, v183
	s_nop 0
	v_cndmask_b32_e32 v183, v183, v182, vcc
	s_add_u32 s30, s30, 0x80
	s_addc_u32 s31, s31, 0
	s_cmpk_lg_i32 s30, 0x180
	s_cbranch_scc1 .LBB0_428
	s_waitcnt lgkmcnt(0)
	s_barrier
	ds_read_b128 v[224:227], v184
	ds_read_b128 v[228:231], v184 offset:1024
	ds_read_b128 v[232:235], v184 offset:2048
	ds_read_b128 v[236:239], v184 offset:3072
	ds_read_b128 v[190:193], v185
	ds_read_b128 v[194:197], v185 offset:1024
	ds_read_b128 v[198:201], v185 offset:2048
	ds_read_b128 v[204:207], v185 offset:3072
	ds_read_b128 v[208:211], v185 offset:4096
	ds_read_b128 v[212:215], v185 offset:5120
	ds_read_b128 v[216:219], v185 offset:6144
	ds_read_b128 v[220:223], v185 offset:7168
	s_movk_i32 vcc_lo, 0x6000
	s_cmp_eq_u32 m0, 2
	s_cselect_b32 vcc_lo, 0xffff4000, vcc_lo
	s_add_u32 m0, m0, 1
	s_cmp_eq_u32 m0, 3
	s_cselect_b32 m0, 0, m0
	v_add_u32_e32 v185, vcc_lo, v185
	v_add_u32_e32 v184, vcc_lo, v184
	v_xor_b32_e32 v185, 64, v185
	v_xor_b32_e32 v184, 64, v184
	s_waitcnt lgkmcnt(7)
	v_mfma_f32_16x16x32_bf16 v[172:175], v[224:227], v[190:193], v[172:175]
	v_mfma_f32_16x16x32_bf16 v[168:171], v[228:231], v[190:193], v[168:171]
	v_mfma_f32_16x16x32_bf16 v[164:167], v[232:235], v[190:193], v[164:167]
	v_mfma_f32_16x16x32_bf16 v[160:163], v[236:239], v[190:193], v[160:163]
	ds_read_b128 v[190:193], v185
	s_waitcnt lgkmcnt(7)
	v_mfma_f32_16x16x32_bf16 v[156:159], v[224:227], v[194:197], v[156:159]
	v_mfma_f32_16x16x32_bf16 v[152:155], v[228:231], v[194:197], v[152:155]
	v_mfma_f32_16x16x32_bf16 v[148:151], v[232:235], v[194:197], v[148:151]
	v_mfma_f32_16x16x32_bf16 v[144:147], v[236:239], v[194:197], v[144:147]
	ds_read_b128 v[194:197], v185 offset:1024
	s_waitcnt lgkmcnt(7)
	v_mfma_f32_16x16x32_bf16 v[136:139], v[224:227], v[198:201], v[136:139]
	v_mfma_f32_16x16x32_bf16 v[132:135], v[228:231], v[198:201], v[132:135]
	v_mfma_f32_16x16x32_bf16 v[128:131], v[232:235], v[198:201], v[128:131]
	v_mfma_f32_16x16x32_bf16 v[124:127], v[236:239], v[198:201], v[124:127]
	ds_read_b128 v[198:201], v185 offset:2048
	s_waitcnt lgkmcnt(7)
	v_mfma_f32_16x16x32_bf16 v[120:123], v[224:227], v[204:207], v[120:123]
	v_mfma_f32_16x16x32_bf16 v[108:111], v[228:231], v[204:207], v[108:111]
	v_mfma_f32_16x16x32_bf16 v[100:103], v[232:235], v[204:207], v[100:103]
	v_mfma_f32_16x16x32_bf16 v[96:99], v[236:239], v[204:207], v[96:99]
	ds_read_b128 v[204:207], v185 offset:3072
	s_waitcnt lgkmcnt(7)
	v_mfma_f32_16x16x32_bf16 v[88:91], v[224:227], v[208:211], v[88:91]
	v_mfma_f32_16x16x32_bf16 v[80:83], v[228:231], v[208:211], v[80:83]
	v_mfma_f32_16x16x32_bf16 v[76:79], v[232:235], v[208:211], v[76:79]
	v_mfma_f32_16x16x32_bf16 v[64:67], v[236:239], v[208:211], v[64:67]
	ds_read_b128 v[208:211], v185 offset:4096
	s_waitcnt lgkmcnt(7)
	v_mfma_f32_16x16x32_bf16 v[60:63], v[224:227], v[212:215], v[60:63]
	v_mfma_f32_16x16x32_bf16 v[52:55], v[228:231], v[212:215], v[52:55]
	v_mfma_f32_16x16x32_bf16 v[44:47], v[232:235], v[212:215], v[44:47]
	v_mfma_f32_16x16x32_bf16 v[36:39], v[236:239], v[212:215], v[36:39]
	ds_read_b128 v[212:215], v185 offset:5120
	s_waitcnt lgkmcnt(7)
	v_mfma_f32_16x16x32_bf16 v[32:35], v[224:227], v[216:219], v[32:35]
	v_mfma_f32_16x16x32_bf16 v[28:31], v[228:231], v[216:219], v[28:31]
	v_mfma_f32_16x16x32_bf16 v[16:19], v[232:235], v[216:219], v[16:19]
	v_mfma_f32_16x16x32_bf16 v[12:15], v[236:239], v[216:219], v[12:15]
	ds_read_b128 v[216:219], v185 offset:6144
	s_waitcnt lgkmcnt(7)
	v_mfma_f32_16x16x32_bf16 v[8:11], v[224:227], v[220:223], v[8:11]
	v_mfma_f32_16x16x32_bf16 v[4:7], v[228:231], v[220:223], v[4:7]
	v_mfma_f32_16x16x32_bf16 v[0:3], v[232:235], v[220:223], v[0:3]
	v_mfma_f32_16x16x32_bf16 v[140:143], v[236:239], v[220:223], v[140:143]
	ds_read_b128 v[220:223], v185 offset:7168
	ds_read_b128 v[224:227], v184
	ds_read_b128 v[228:231], v184 offset:1024
	ds_read_b128 v[232:235], v184 offset:2048
	ds_read_b128 v[236:239], v184 offset:3072
	s_movk_i32 vcc_lo, 0x6000
	s_cmp_eq_u32 m0, 2
	s_cselect_b32 vcc_lo, 0xffff4000, vcc_lo
	s_add_u32 m0, m0, 1
	s_cmp_eq_u32 m0, 3
	s_cselect_b32 m0, 0, m0
	v_add_u32_e32 v185, vcc_lo, v185
	v_add_u32_e32 v184, vcc_lo, v184
	v_xor_b32_e32 v185, 64, v185
	v_xor_b32_e32 v184, 64, v184
	s_waitcnt lgkmcnt(0)
	v_mfma_f32_16x16x32_bf16 v[172:175], v[224:227], v[190:193], v[172:175]
	v_mfma_f32_16x16x32_bf16 v[168:171], v[228:231], v[190:193], v[168:171]
	v_mfma_f32_16x16x32_bf16 v[164:167], v[232:235], v[190:193], v[164:167]
	v_mfma_f32_16x16x32_bf16 v[160:163], v[236:239], v[190:193], v[160:163]
	v_mfma_f32_16x16x32_bf16 v[156:159], v[224:227], v[194:197], v[156:159]
	v_mfma_f32_16x16x32_bf16 v[152:155], v[228:231], v[194:197], v[152:155]
	v_mfma_f32_16x16x32_bf16 v[148:151], v[232:235], v[194:197], v[148:151]
	v_mfma_f32_16x16x32_bf16 v[144:147], v[236:239], v[194:197], v[144:147]
	v_mfma_f32_16x16x32_bf16 v[136:139], v[224:227], v[198:201], v[136:139]
	v_mfma_f32_16x16x32_bf16 v[132:135], v[228:231], v[198:201], v[132:135]
	v_mfma_f32_16x16x32_bf16 v[128:131], v[232:235], v[198:201], v[128:131]
	v_mfma_f32_16x16x32_bf16 v[124:127], v[236:239], v[198:201], v[124:127]
	v_mfma_f32_16x16x32_bf16 v[120:123], v[224:227], v[204:207], v[120:123]
	v_mfma_f32_16x16x32_bf16 v[108:111], v[228:231], v[204:207], v[108:111]
	v_mfma_f32_16x16x32_bf16 v[100:103], v[232:235], v[204:207], v[100:103]
	v_mfma_f32_16x16x32_bf16 v[96:99], v[236:239], v[204:207], v[96:99]
	v_mfma_f32_16x16x32_bf16 v[88:91], v[224:227], v[208:211], v[88:91]
	v_mfma_f32_16x16x32_bf16 v[80:83], v[228:231], v[208:211], v[80:83]
	v_mfma_f32_16x16x32_bf16 v[76:79], v[232:235], v[208:211], v[76:79]
	v_mfma_f32_16x16x32_bf16 v[64:67], v[236:239], v[208:211], v[64:67]
	v_mfma_f32_16x16x32_bf16 v[60:63], v[224:227], v[212:215], v[60:63]
	v_mfma_f32_16x16x32_bf16 v[52:55], v[228:231], v[212:215], v[52:55]
	v_mfma_f32_16x16x32_bf16 v[44:47], v[232:235], v[212:215], v[44:47]
	v_mfma_f32_16x16x32_bf16 v[36:39], v[236:239], v[212:215], v[36:39]
	v_mfma_f32_16x16x32_bf16 v[32:35], v[224:227], v[216:219], v[32:35]
	v_mfma_f32_16x16x32_bf16 v[28:31], v[228:231], v[216:219], v[28:31]
	v_mfma_f32_16x16x32_bf16 v[16:19], v[232:235], v[216:219], v[16:19]
	v_mfma_f32_16x16x32_bf16 v[12:15], v[236:239], v[216:219], v[12:15]
	v_mfma_f32_16x16x32_bf16 v[8:11], v[224:227], v[220:223], v[8:11]
	v_mfma_f32_16x16x32_bf16 v[4:7], v[228:231], v[220:223], v[4:7]
	v_mfma_f32_16x16x32_bf16 v[0:3], v[232:235], v[220:223], v[0:3]
	v_mfma_f32_16x16x32_bf16 v[140:143], v[236:239], v[220:223], v[140:143]
	v_lshrrev_b32_e32 v224, 4, v188
	v_and_b32_e32 v225, 7, v188
	v_bitop3_b32 v226, v224, v225, 3 bitop3:0x6c
	v_lshlrev_b32_e32 v227, 7, v188
	v_bfe_u32 v228, v188, 4, 2
	v_and_b32_e32 v229, 0xffffc780, v227
	v_and_b32_e32 v227, 0x2780, v227
	v_bitop3_b32 v228, v228, v225, 4 bitop3:0x36
	v_lshlrev_b32_e32 v226, 4, v226
	v_lshlrev_b32_e32 v228, 4, v228
	v_or_b32_e32 v185, v229, v226
	v_or_b32_e32 v184, v227, v226
	v_or_b32_e32 v183, v229, v228
	v_or_b32_e32 v182, v227, v228
	s_waitcnt vmcnt(0)
	s_barrier
	s_waitcnt vmcnt(10)
	ds_write_b128 v176, v[116:119]
	s_waitcnt vmcnt(9)
	ds_write_b128 v176, v[112:115] offset:4096
	s_waitcnt vmcnt(8)
	ds_write_b128 v176, v[104:107] offset:8192
	s_waitcnt vmcnt(7)
	ds_write_b128 v176, v[92:95] offset:12288
	s_waitcnt vmcnt(6)
	ds_write_b128 v176, v[84:87] offset:16384
	s_waitcnt vmcnt(5)
	ds_write_b128 v176, v[72:75] offset:20480
	s_waitcnt vmcnt(4)
	ds_write_b128 v176, v[68:71] offset:24576
	s_waitcnt vmcnt(3)
	ds_write_b128 v176, v[48:51] offset:28672
	ds_write_b128 v176, v[56:59] offset:32768
	s_waitcnt vmcnt(2)
	ds_write_b128 v176, v[40:43] offset:36864
	s_waitcnt vmcnt(1)
	ds_write_b128 v176, v[24:27] offset:40960
	s_waitcnt vmcnt(0)
	ds_write_b128 v176, v[20:23] offset:45056
	s_waitcnt lgkmcnt(0)
	s_barrier
	ds_read_b128 v[20:23], v185
	ds_read_b128 v[24:27], v185 offset:2048
	ds_read_b128 v[40:43], v185 offset:4096
	ds_read_b128 v[48:51], v185 offset:6144
	ds_read_b128 v[56:59], v185 offset:8192
	ds_read_b128 v[68:71], v185 offset:10240
	ds_read_b128 v[72:75], v185 offset:12288
	ds_read_b128 v[84:87], v185 offset:14336
	ds_read_b128 v[92:95], v184 offset:32768
	ds_read_b128 v[104:107], v184 offset:34816
	ds_read_b128 v[112:115], v184 offset:36864
	ds_read_b128 v[116:119], v184 offset:38912
	s_waitcnt lgkmcnt(3)
	v_mfma_f32_16x16x32_bf16 v[172:175], v[92:95], v[20:23], v[172:175]
	s_waitcnt lgkmcnt(2)
	v_mfma_f32_16x16x32_bf16 v[168:171], v[104:107], v[20:23], v[168:171]
	s_waitcnt lgkmcnt(1)
	v_mfma_f32_16x16x32_bf16 v[164:167], v[112:115], v[20:23], v[164:167]
	s_waitcnt lgkmcnt(0)
	v_mfma_f32_16x16x32_bf16 v[20:23], v[116:119], v[20:23], v[160:163]
	v_mfma_f32_16x16x32_bf16 v[156:159], v[92:95], v[24:27], v[156:159]
	v_mfma_f32_16x16x32_bf16 v[152:155], v[104:107], v[24:27], v[152:155]
	v_mfma_f32_16x16x32_bf16 v[148:151], v[112:115], v[24:27], v[148:151]
	v_mfma_f32_16x16x32_bf16 v[24:27], v[116:119], v[24:27], v[144:147]
	v_mfma_f32_16x16x32_bf16 v[136:139], v[92:95], v[40:43], v[136:139]
	v_mfma_f32_16x16x32_bf16 v[132:135], v[104:107], v[40:43], v[132:135]
	v_mfma_f32_16x16x32_bf16 v[128:131], v[112:115], v[40:43], v[128:131]
	v_mfma_f32_16x16x32_bf16 v[40:43], v[116:119], v[40:43], v[124:127]
	v_mfma_f32_16x16x32_bf16 v[144:147], v[92:95], v[48:51], v[120:123]
	v_mfma_f32_16x16x32_bf16 v[160:163], v[104:107], v[48:51], v[108:111]
	v_mfma_f32_16x16x32_bf16 v[178:181], v[112:115], v[48:51], v[100:103]
	v_mfma_f32_16x16x32_bf16 v[48:51], v[116:119], v[48:51], v[96:99]
	v_mfma_f32_16x16x32_bf16 v[16:19], v[112:115], v[72:75], v[16:19]
	v_mfma_f32_16x16x32_bf16 v[12:15], v[116:119], v[72:75], v[12:15]
	v_mfma_f32_16x16x32_bf16 v[8:11], v[92:95], v[84:87], v[8:11]
	v_mfma_f32_16x16x32_bf16 v[4:7], v[104:107], v[84:87], v[4:7]
	v_mfma_f32_16x16x32_bf16 v[0:3], v[112:115], v[84:87], v[0:3]
	v_mfma_f32_16x16x32_bf16 v[184:187], v[92:95], v[56:59], v[88:91]
	v_mfma_f32_16x16x32_bf16 v[190:193], v[104:107], v[56:59], v[80:83]
	v_mfma_f32_16x16x32_bf16 v[194:197], v[112:115], v[56:59], v[76:79]
	v_mfma_f32_16x16x32_bf16 v[198:201], v[116:119], v[56:59], v[64:67]
	v_mfma_f32_16x16x32_bf16 v[204:207], v[92:95], v[68:71], v[60:63]
	v_mfma_f32_16x16x32_bf16 v[208:211], v[104:107], v[68:71], v[52:55]
	v_mfma_f32_16x16x32_bf16 v[212:215], v[112:115], v[68:71], v[44:47]
	v_mfma_f32_16x16x32_bf16 v[216:219], v[116:119], v[68:71], v[36:39]
	v_mfma_f32_16x16x32_bf16 v[220:223], v[92:95], v[72:75], v[32:35]
	v_mfma_f32_16x16x32_bf16 v[224:227], v[104:107], v[72:75], v[28:31]
	v_mfma_f32_16x16x32_bf16 v[140:143], v[116:119], v[84:87], v[140:143]
	s_nop 1
	ds_read_b128 v[28:31], v183
	ds_read_b128 v[32:35], v183 offset:2048
	ds_read_b128 v[36:39], v183 offset:4096
	ds_read_b128 v[44:47], v183 offset:6144
	ds_read_b128 v[228:231], v183 offset:8192
	ds_read_b128 v[232:235], v183 offset:10240
	ds_read_b128 v[236:239], v183 offset:12288
	ds_read_b128 v[240:243], v183 offset:14336
	ds_read_b128 v[244:247], v182 offset:32768
	ds_read_b128 v[248:251], v182 offset:34816
	ds_read_b128 v[52:55], v182 offset:36864
	ds_read_b128 v[56:59], v182 offset:38912
	s_waitcnt lgkmcnt(3)
	v_mfma_f32_16x16x32_bf16 v[124:127], v[244:247], v[28:31], v[172:175]
	v_readlane_b32 s16, v255, 27
	v_readlane_b32 s17, v255, 28
	v_readlane_b32 s11, v255, 16
	s_waitcnt lgkmcnt(2)
	v_mfma_f32_16x16x32_bf16 v[120:123], v[248:251], v[28:31], v[168:171]
	v_readlane_b32 s10, v255, 18
	s_waitcnt lgkmcnt(1)
	v_mfma_f32_16x16x32_bf16 v[116:119], v[52:55], v[28:31], v[164:167]
	s_waitcnt lgkmcnt(0)
	v_mfma_f32_16x16x32_bf16 v[112:115], v[56:59], v[28:31], v[20:23]
	v_mfma_f32_16x16x32_bf16 v[108:111], v[244:247], v[32:35], v[156:159]
	v_mfma_f32_16x16x32_bf16 v[104:107], v[248:251], v[32:35], v[152:155]
	v_mfma_f32_16x16x32_bf16 v[100:103], v[52:55], v[32:35], v[148:151]
	v_mfma_f32_16x16x32_bf16 v[96:99], v[56:59], v[32:35], v[24:27]
	v_mfma_f32_16x16x32_bf16 v[92:95], v[244:247], v[36:39], v[136:139]
	v_mfma_f32_16x16x32_bf16 v[88:91], v[248:251], v[36:39], v[132:135]
	v_mfma_f32_16x16x32_bf16 v[84:87], v[52:55], v[36:39], v[128:131]
	v_mfma_f32_16x16x32_bf16 v[80:83], v[56:59], v[36:39], v[40:43]
	v_mfma_f32_16x16x32_bf16 v[76:79], v[244:247], v[44:47], v[144:147]
	v_mfma_f32_16x16x32_bf16 v[72:75], v[248:251], v[44:47], v[160:163]
	v_mfma_f32_16x16x32_bf16 v[68:71], v[52:55], v[44:47], v[178:181]
	v_mfma_f32_16x16x32_bf16 v[64:67], v[56:59], v[44:47], v[48:51]
	v_mfma_f32_16x16x32_bf16 v[60:63], v[244:247], v[228:231], v[184:187]
	v_mfma_f32_16x16x32_bf16 v[156:159], v[248:251], v[228:231], v[190:193]
	v_mfma_f32_16x16x32_bf16 v[152:155], v[52:55], v[228:231], v[194:197]
	v_mfma_f32_16x16x32_bf16 v[48:51], v[56:59], v[228:231], v[198:201]
	v_mfma_f32_16x16x32_bf16 v[44:47], v[244:247], v[232:235], v[204:207]
	v_mfma_f32_16x16x32_bf16 v[40:43], v[248:251], v[232:235], v[208:211]
	v_mfma_f32_16x16x32_bf16 v[36:39], v[52:55], v[232:235], v[212:215]
	v_mfma_f32_16x16x32_bf16 v[32:35], v[56:59], v[232:235], v[216:219]
	v_mfma_f32_16x16x32_bf16 v[28:31], v[244:247], v[236:239], v[220:223]
	v_mfma_f32_16x16x32_bf16 v[24:27], v[248:251], v[236:239], v[224:227]
	v_mfma_f32_16x16x32_bf16 v[20:23], v[52:55], v[236:239], v[16:19]
	v_mfma_f32_16x16x32_bf16 v[16:19], v[56:59], v[236:239], v[12:15]
	v_mfma_f32_16x16x32_bf16 v[12:15], v[244:247], v[240:243], v[8:11]
	v_mfma_f32_16x16x32_bf16 v[8:11], v[248:251], v[240:243], v[4:7]
	v_mfma_f32_16x16x32_bf16 v[0:3], v[52:55], v[240:243], v[0:3]
	v_mfma_f32_16x16x32_bf16 v[4:7], v[56:59], v[240:243], v[140:143]
	v_xor_b32_e32 v240, 32, v203
